# final candidate re-measure: combined LDS-image layouts (U, w_up, w_down) + whole-line PROJ stores
# baseline (speedup 1.0000x reference)
.LBB0_15:
	v_cvt_f32_u32_e32 v1, s40
	s_mov_b32 s35, 1
	s_mov_b32 s0, 1
	s_mov_b32 s11, 3
	v_rcp_iflag_f32_e32 v4, v1
	s_mov_b32 s1, 1
	s_cmp_gt_i32 s35, 0
	v_writelane_b32 v250, s1, 3
	v_writelane_b32 v250, s0, 4
	s_cbranch_scc1 .LBB0_17
	v_mul_f32_e32 v1, 0x4f7ffffe, v4
	s_abs_i32 s34, s40
	v_cvt_u32_f32_e32 v1, v1
	v_cvt_f32_u32_e32 v3, s34
	s_lshl_b32 s0, s82, 9
	v_writelane_b32 v250, s0, 5
	v_readfirstlane_b32 s1, v1
	v_rcp_iflag_f32_e32 v1, v3
	s_sub_i32 s0, 0, s40
	s_mul_i32 s0, s0, s1
	s_mul_hi_u32 s0, s1, s0
	v_mul_f32_e32 v1, 0x4f7ffffe, v1
	v_cvt_u32_f32_e32 v1, v1
	s_add_i32 s72, s1, s0
	s_sub_i32 s0, 0, s34
	s_mov_b32 s5, 0
	v_readfirstlane_b32 s1, v1
	s_mul_i32 s0, s0, s1
	s_mul_hi_u32 s0, s1, s0
	s_lshl_b32 s4, s33, 6
	s_lshl_b32 s60, s40, 9
	s_mov_b32 s73, s5
	s_ashr_i32 s18, s40, 31
	s_add_i32 s20, s1, s0
	s_mov_b32 s21, s5
	s_mov_b64 s[0:1], 0
	s_branch .LBB0_18

.LBB0_322:
	s_add_i32 s20, s19, s16
	s_cmpk_gt_i32 s20, 0x5aff
	s_cbranch_scc1 .LBB0_321
	s_cmpk_gt_i32 s20, 0x12ff
	s_mov_b64 s[16:17], -1
	s_cbranch_scc0 .LBB0_333
	s_cmpk_gt_u32 s20, 0x1aff
	s_cbranch_scc0 .LBB0_330
	s_cmpk_gt_u32 s20, 0x3aff
	s_cbranch_scc0 .LBB0_327
	s_and_b32 s16, s20, 0x7fffffc0
	s_addk_i32 s16, 0xc500
	s_lshl_b32 s17, s20, 5
	s_and_b32 s21, s17, 0x7e0
	v_add_u32_e32 v20, s16, v1
	s_lshl_b32 s90, s21, 2
	v_ashrrev_i32_e32 v21, 31, v20
	v_lshl_add_u64 v[22:23], v[4:5], 0, s[90:91]
	v_lshlrev_b64 v[20:21], 13, v[20:21]
	v_lshl_add_u64 v[20:21], v[22:23], 0, v[20:21]
	v_add_co_u32_e32 v22, vcc, 0x4000, v20
	global_load_dword v9, v[20:21], off nt
	s_nop 0
	v_addc_co_u32_e32 v23, vcc, 0, v21, vcc
	global_load_dword v18, v[22:23], off nt
	v_add_co_u32_e32 v22, vcc, 0x8000, v20
	s_mov_b32 s17, 0xc000
	s_nop 0
	v_addc_co_u32_e32 v23, vcc, 0, v21, vcc
	global_load_dword v30, v[22:23], off nt
	v_add_co_u32_e32 v22, vcc, s17, v20
	s_mov_b32 s17, 0x10000
	s_nop 0
	v_addc_co_u32_e32 v23, vcc, 0, v21, vcc
	global_load_dword v31, v[22:23], off nt
	v_add_co_u32_e32 v22, vcc, s17, v20
	s_mov_b32 s17, 0x14000
	s_nop 0
	v_addc_co_u32_e32 v23, vcc, 0, v21, vcc
	global_load_dword v32, v[22:23], off nt
	v_add_co_u32_e32 v22, vcc, s17, v20
	s_mov_b32 s17, 0x18000
	s_nop 0
	v_addc_co_u32_e32 v23, vcc, 0, v21, vcc
	global_load_dword v33, v[22:23], off nt
	v_add_co_u32_e32 v22, vcc, s17, v20
	s_mov_b32 s17, 0x1c000
	s_nop 0
	v_addc_co_u32_e32 v23, vcc, 0, v21, vcc
	global_load_dword v34, v[22:23], off nt
	v_add_co_u32_e32 v22, vcc, s17, v20
	s_mov_b32 s17, 0x20000
	s_nop 0
	v_addc_co_u32_e32 v23, vcc, 0, v21, vcc
	global_load_dword v35, v[22:23], off nt
	v_add_co_u32_e32 v22, vcc, s17, v20
	s_mov_b32 s17, 0x24000
	s_nop 0
	v_addc_co_u32_e32 v23, vcc, 0, v21, vcc
	global_load_dword v36, v[22:23], off nt
	v_add_co_u32_e32 v22, vcc, s17, v20
	s_mov_b32 s17, 0x28000
	s_nop 0
	v_addc_co_u32_e32 v23, vcc, 0, v21, vcc
	global_load_dword v37, v[22:23], off nt
	v_add_co_u32_e32 v22, vcc, s17, v20
	s_mov_b32 s17, 0x2c000
	s_nop 0
	v_addc_co_u32_e32 v23, vcc, 0, v21, vcc
	global_load_dword v38, v[22:23], off nt
	v_add_co_u32_e32 v22, vcc, s17, v20
	s_mov_b32 s17, 0x30000
	s_nop 0
	v_addc_co_u32_e32 v23, vcc, 0, v21, vcc
	global_load_dword v39, v[22:23], off nt
	v_add_co_u32_e32 v22, vcc, s17, v20
	s_mov_b32 s17, 0x34000
	s_nop 0
	v_addc_co_u32_e32 v23, vcc, 0, v21, vcc
	global_load_dword v40, v[22:23], off nt
	v_add_co_u32_e32 v22, vcc, s17, v20
	s_mov_b32 s17, 0x38000
	s_nop 0
	v_addc_co_u32_e32 v23, vcc, 0, v21, vcc
	global_load_dword v41, v[22:23], off nt
	v_add_co_u32_e32 v22, vcc, s17, v20
	s_mov_b32 s17, 0x3c000
	s_nop 0
	v_addc_co_u32_e32 v23, vcc, 0, v21, vcc
	global_load_dword v42, v[22:23], off nt
	v_add_co_u32_e32 v22, vcc, s17, v20
	s_mov_b32 s17, 0x40000
	s_nop 0
	v_addc_co_u32_e32 v23, vcc, 0, v21, vcc
	global_load_dword v43, v[22:23], off nt
	v_add_co_u32_e32 v22, vcc, s17, v20
	s_mov_b32 s17, 0x44000
	s_nop 0
	v_addc_co_u32_e32 v23, vcc, 0, v21, vcc
	global_load_dword v44, v[22:23], off nt
	v_add_co_u32_e32 v22, vcc, s17, v20
	s_mov_b32 s17, 0x48000
	s_nop 0
	v_addc_co_u32_e32 v23, vcc, 0, v21, vcc
	global_load_dword v45, v[22:23], off nt
	v_add_co_u32_e32 v22, vcc, s17, v20
	s_mov_b32 s17, 0x4c000
	s_nop 0
	v_addc_co_u32_e32 v23, vcc, 0, v21, vcc
	global_load_dword v46, v[22:23], off nt
	v_add_co_u32_e32 v22, vcc, s17, v20
	s_mov_b32 s17, 0x50000
	s_nop 0
	v_addc_co_u32_e32 v23, vcc, 0, v21, vcc
	global_load_dword v47, v[22:23], off nt
	v_add_co_u32_e32 v22, vcc, s17, v20
	s_mov_b32 s17, 0x54000
	s_nop 0
	v_addc_co_u32_e32 v23, vcc, 0, v21, vcc
	global_load_dword v48, v[22:23], off nt
	v_add_co_u32_e32 v22, vcc, s17, v20
	s_mov_b32 s17, 0x58000
	s_nop 0
	v_addc_co_u32_e32 v23, vcc, 0, v21, vcc
	global_load_dword v49, v[22:23], off nt
	v_add_co_u32_e32 v22, vcc, s17, v20
	s_mov_b32 s17, 0x5c000
	s_nop 0
	v_addc_co_u32_e32 v23, vcc, 0, v21, vcc
	global_load_dword v50, v[22:23], off nt
	v_add_co_u32_e32 v22, vcc, s17, v20
	s_mov_b32 s17, 0x60000
	s_nop 0
	v_addc_co_u32_e32 v23, vcc, 0, v21, vcc
	global_load_dword v51, v[22:23], off nt
	v_add_co_u32_e32 v22, vcc, s17, v20
	s_mov_b32 s17, 0x64000
	s_nop 0
	v_addc_co_u32_e32 v23, vcc, 0, v21, vcc
	global_load_dword v52, v[22:23], off nt
	v_add_co_u32_e32 v22, vcc, s17, v20
	s_mov_b32 s17, 0x68000
	s_nop 0
	v_addc_co_u32_e32 v23, vcc, 0, v21, vcc
	global_load_dword v53, v[22:23], off nt
	v_add_co_u32_e32 v22, vcc, s17, v20
	s_mov_b32 s17, 0x6c000
	s_nop 0
	v_addc_co_u32_e32 v23, vcc, 0, v21, vcc
	global_load_dword v54, v[22:23], off nt
	v_add_co_u32_e32 v22, vcc, s17, v20
	s_mov_b32 s17, 0x70000
	s_nop 0
	v_addc_co_u32_e32 v23, vcc, 0, v21, vcc
	global_load_dword v55, v[22:23], off nt
	v_add_co_u32_e32 v22, vcc, s17, v20
	s_mov_b32 s17, 0x74000
	s_nop 0
	v_addc_co_u32_e32 v23, vcc, 0, v21, vcc
	global_load_dword v56, v[22:23], off nt
	v_add_co_u32_e32 v22, vcc, s17, v20
	s_mov_b32 s17, 0x78000
	s_nop 0
	v_addc_co_u32_e32 v23, vcc, 0, v21, vcc
	global_load_dword v57, v[22:23], off nt
	v_add_co_u32_e32 v22, vcc, s17, v20
	s_mov_b32 s17, 0x7c000
	s_nop 0
	v_addc_co_u32_e32 v23, vcc, 0, v21, vcc
	v_add_co_u32_e32 v20, vcc, s17, v20
	global_load_dword v22, v[22:23], off nt
	s_nop 0
	v_addc_co_u32_e32 v21, vcc, 0, v21, vcc
	global_load_dword v20, v[20:21], off nt
	s_waitcnt vmcnt(0)
	ds_write2_b32 v24, v9, v18 offset1:66
	ds_write2_b32 v24, v30, v31 offset0:132 offset1:198
	v_add_u32_e32 v9, 0x400, v24
	ds_write2_b32 v9, v32, v33 offset0:8 offset1:74
	ds_write2_b32 v9, v34, v35 offset0:140 offset1:206
	v_add_u32_e32 v9, 0x800, v24
	ds_write2_b32 v9, v36, v37 offset0:16 offset1:82
	ds_write2_b32 v9, v38, v39 offset0:148 offset1:214
	v_add_u32_e32 v9, 0xc00, v24
	ds_write2_b32 v9, v40, v41 offset0:24 offset1:90
	ds_write2_b32 v9, v42, v43 offset0:156 offset1:222
	v_add_u32_e32 v9, 0x1000, v24
	ds_write2_b32 v9, v44, v45 offset0:32 offset1:98
	ds_write2_b32 v9, v46, v47 offset0:164 offset1:230
	v_add_u32_e32 v9, 0x1400, v24
	ds_write2_b32 v9, v48, v49 offset0:40 offset1:106
	ds_write2_b32 v9, v50, v51 offset0:172 offset1:238
	v_add_u32_e32 v9, 0x1800, v24
	ds_write2_b32 v9, v52, v53 offset0:48 offset1:114
	ds_write2_b32 v9, v54, v55 offset0:180 offset1:246
	v_add_u32_e32 v9, 0x1c00, v24
	ds_write2_b32 v9, v56, v57 offset0:56 offset1:122
	ds_write2_b32 v9, v22, v20 offset0:188 offset1:254
	s_waitcnt lgkmcnt(0)
	ds_read2_b32 v[30:31], v26 offset0:33 offset1:41
	ds_read2_b32 v[32:33], v26 offset1:8
	ds_read2_b32 v[34:35], v26 offset0:66 offset1:74
	ds_read2_b32 v[36:37], v26 offset0:99 offset1:107
	ds_read2_b32 v[38:39], v26 offset0:132 offset1:140
	ds_read2_b32 v[40:41], v26 offset0:165 offset1:173
	ds_read2_b32 v[42:43], v26 offset0:198 offset1:206
	ds_read2_b32 v[44:45], v26 offset0:231 offset1:239
	s_waitcnt lgkmcnt(7)
	v_bfe_u32 v18, v30, 16, 1
	s_waitcnt lgkmcnt(6)
	v_bfe_u32 v9, v32, 16, 1
	v_add3_u32 v9, v32, v9, s79
	v_lshrrev_b32_e32 v9, 16, v9
	v_add3_u32 v18, v30, v18, s79
	v_and_or_b32 v20, v18, s80, v9
	s_waitcnt lgkmcnt(5)
	v_bfe_u32 v9, v34, 16, 1
	v_add3_u32 v9, v34, v9, s79
	s_waitcnt lgkmcnt(4)
	v_bfe_u32 v18, v36, 16, 1
	v_lshrrev_b32_e32 v9, 16, v9
	v_add3_u32 v18, v36, v18, s79
	v_and_or_b32 v21, v18, s80, v9
	s_waitcnt lgkmcnt(3)
	v_bfe_u32 v9, v38, 16, 1
	v_add3_u32 v9, v38, v9, s79
	s_waitcnt lgkmcnt(2)
	v_bfe_u32 v18, v40, 16, 1
	v_lshrrev_b32_e32 v9, 16, v9
	v_add3_u32 v18, v40, v18, s79
	v_and_or_b32 v22, v18, s80, v9
	s_waitcnt lgkmcnt(1)
	v_bfe_u32 v9, v42, 16, 1
	v_add3_u32 v9, v42, v9, s79
	s_waitcnt lgkmcnt(0)
	v_bfe_u32 v18, v44, 16, 1
	v_lshrrev_b32_e32 v9, 16, v9
	v_add3_u32 v18, v44, v18, s79
	v_and_or_b32 v23, v18, s80, v9
	v_add_u32_e32 v9, s21, v25
	v_ashrrev_i32_e32 v46, 8, v9
	v_ashrrev_i32_e32 v47, 31, v46
	s_lshr_b32 s90, s16, 6
	v_lshlrev_b64 v[46:47], 22, v[46:47]
	s_lshl_b64 s[16:17], s[90:91], 15
	v_lshl_add_u64 v[46:47], s[0:1], 0, v[46:47]
	v_lshlrev_b32_e32 v9, 7, v9
	v_lshl_add_u64 v[46:47], v[46:47], 0, s[16:17]
	v_and_b32_e32 v18, 0x7f80, v9
	v_lshl_add_u64 v[46:47], v[46:47], 0, v[18:19]
	v_mov_b32_e32 v9, v19
	v_lshl_add_u64 v[46:47], v[46:47], 0, v[8:9]
	v_bfe_u32 v18, v33, 16, 1
	global_store_dwordx4 v[46:47], v[20:23], off
	v_add3_u32 v18, v33, v18, s79
	v_lshrrev_b32_e32 v18, 16, v18
	v_bfe_u32 v20, v31, 16, 1
	v_add3_u32 v20, v31, v20, s79
	v_and_or_b32 v20, v20, s80, v18
	v_bfe_u32 v18, v35, 16, 1
	v_add3_u32 v18, v35, v18, s79
	v_bfe_u32 v21, v37, 16, 1
	v_lshrrev_b32_e32 v18, 16, v18
	v_add3_u32 v21, v37, v21, s79
	v_and_or_b32 v21, v21, s80, v18
	v_bfe_u32 v18, v39, 16, 1
	v_add3_u32 v18, v39, v18, s79
	v_bfe_u32 v22, v41, 16, 1
	v_lshrrev_b32_e32 v18, 16, v18
	v_add3_u32 v22, v41, v22, s79
	v_and_or_b32 v22, v22, s80, v18
	v_bfe_u32 v18, v43, 16, 1
	v_add3_u32 v18, v43, v18, s79
	v_bfe_u32 v23, v45, 16, 1
	v_lshrrev_b32_e32 v18, 16, v18
	v_add3_u32 v23, v45, v23, s79
	v_and_or_b32 v23, v23, s80, v18
	v_add_u32_e32 v18, s21, v27
	v_ashrrev_i32_e32 v30, 8, v18
	v_ashrrev_i32_e32 v31, 31, v30
	v_lshlrev_b64 v[30:31], 22, v[30:31]
	v_lshl_add_u64 v[30:31], s[0:1], 0, v[30:31]
	v_lshlrev_b32_e32 v18, 7, v18
	v_lshl_add_u64 v[30:31], v[30:31], 0, s[16:17]
	v_and_b32_e32 v18, 0x7f80, v18
	v_lshl_add_u64 v[30:31], v[30:31], 0, v[18:19]
	v_lshl_add_u64 v[30:31], v[30:31], 0, v[8:9]
	global_store_dwordx4 v[30:31], v[20:23], off
	ds_read2_b32 v[30:31], v26 offset0:16 offset1:24
	ds_read2_b32 v[32:33], v26 offset0:49 offset1:57
	ds_read2_b32 v[34:35], v26 offset0:82 offset1:90
	ds_read2_b32 v[36:37], v26 offset0:115 offset1:123
	ds_read2_b32 v[38:39], v26 offset0:148 offset1:156
	ds_read2_b32 v[40:41], v26 offset0:181 offset1:189
	ds_read2_b32 v[42:43], v26 offset0:214 offset1:222
	ds_read2_b32 v[44:45], v26 offset0:247 offset1:255
	s_waitcnt lgkmcnt(7)
	v_bfe_u32 v18, v30, 16, 1
	v_add3_u32 v18, v30, v18, s79
	s_waitcnt lgkmcnt(6)
	v_bfe_u32 v20, v32, 16, 1
	v_lshrrev_b32_e32 v18, 16, v18
	v_add3_u32 v20, v32, v20, s79
	v_and_or_b32 v20, v20, s80, v18
	s_waitcnt lgkmcnt(5)
	v_bfe_u32 v18, v34, 16, 1
	v_add3_u32 v18, v34, v18, s79
	s_waitcnt lgkmcnt(4)
	v_bfe_u32 v21, v36, 16, 1
	v_lshrrev_b32_e32 v18, 16, v18
	v_add3_u32 v21, v36, v21, s79
	v_and_or_b32 v21, v21, s80, v18
	s_waitcnt lgkmcnt(3)
	v_bfe_u32 v18, v38, 16, 1
	v_add3_u32 v18, v38, v18, s79
	s_waitcnt lgkmcnt(2)
	v_bfe_u32 v22, v40, 16, 1
	v_lshrrev_b32_e32 v18, 16, v18
	v_add3_u32 v22, v40, v22, s79
	v_and_or_b32 v22, v22, s80, v18
	s_waitcnt lgkmcnt(1)
	v_bfe_u32 v18, v42, 16, 1
	v_add3_u32 v18, v42, v18, s79
	s_waitcnt lgkmcnt(0)
	v_bfe_u32 v23, v44, 16, 1
	v_lshrrev_b32_e32 v18, 16, v18
	v_add3_u32 v23, v44, v23, s79
	v_and_or_b32 v23, v23, s80, v18
	v_add_u32_e32 v18, s21, v28
	v_ashrrev_i32_e32 v46, 8, v18
	v_ashrrev_i32_e32 v47, 31, v46
	v_lshlrev_b64 v[46:47], 22, v[46:47]
	v_lshl_add_u64 v[46:47], s[0:1], 0, v[46:47]
	v_lshlrev_b32_e32 v18, 7, v18
	v_lshl_add_u64 v[46:47], v[46:47], 0, s[16:17]
	v_and_b32_e32 v18, 0x7f80, v18
	v_lshl_add_u64 v[46:47], v[46:47], 0, v[18:19]
	v_lshl_add_u64 v[46:47], v[46:47], 0, v[8:9]
	v_bfe_u32 v18, v31, 16, 1
	global_store_dwordx4 v[46:47], v[20:23], off
	v_add3_u32 v18, v31, v18, s79
	v_lshrrev_b32_e32 v18, 16, v18
	v_bfe_u32 v20, v33, 16, 1
	v_add3_u32 v20, v33, v20, s79
	v_and_or_b32 v20, v20, s80, v18
	v_bfe_u32 v18, v35, 16, 1
	v_add3_u32 v18, v35, v18, s79
	v_bfe_u32 v21, v37, 16, 1
	v_lshrrev_b32_e32 v18, 16, v18
	v_add3_u32 v21, v37, v21, s79
	v_and_or_b32 v21, v21, s80, v18
	v_bfe_u32 v18, v39, 16, 1
	v_add3_u32 v18, v39, v18, s79
	v_bfe_u32 v22, v41, 16, 1
	v_lshrrev_b32_e32 v18, 16, v18
	v_add3_u32 v22, v41, v22, s79
	v_and_or_b32 v22, v22, s80, v18
	v_bfe_u32 v18, v43, 16, 1
	v_add3_u32 v18, v43, v18, s79
	v_bfe_u32 v23, v45, 16, 1
	v_lshrrev_b32_e32 v18, 16, v18
	v_add3_u32 v23, v45, v23, s79
	v_and_or_b32 v23, v23, s80, v18
	v_add_u32_e32 v18, s21, v29
	v_ashrrev_i32_e32 v30, 8, v18
	v_ashrrev_i32_e32 v31, 31, v30
	v_lshlrev_b64 v[30:31], 22, v[30:31]
	v_lshl_add_u64 v[30:31], s[0:1], 0, v[30:31]
	v_lshlrev_b32_e32 v18, 7, v18
	v_lshl_add_u64 v[30:31], v[30:31], 0, s[16:17]
	v_and_b32_e32 v18, 0x7f80, v18
	v_lshl_add_u64 v[30:31], v[30:31], 0, v[18:19]
	v_lshl_add_u64 v[30:31], v[30:31], 0, v[8:9]
	global_store_dwordx4 v[30:31], v[20:23], off
	s_waitcnt lgkmcnt(0)
	s_mov_b64 s[16:17], 0
.LBB0_327:
	s_andn2_b64 vcc, exec, s[16:17]
	s_cbranch_vccnz .LBB0_329
	s_add_i32 s16, s20, 0xffffe500
	s_lshr_b32 s16, s16, 2
	s_and_b32 s17, s16, 0x3fffffc0
	s_lshl_b32 s16, s20, 5
	s_and_b32 s16, s16, 0x1fe0
	v_add_u32_e32 v20, s17, v1
	s_lshl_b32 s90, s16, 2
	v_ashrrev_i32_e32 v21, 31, v20
	v_lshl_add_u64 v[22:23], v[6:7], 0, s[90:91]
	v_lshlrev_b64 v[20:21], 15, v[20:21]
	v_lshl_add_u64 v[20:21], v[22:23], 0, v[20:21]
	v_add_co_u32_e32 v22, vcc, 0x10000, v20
	global_load_dword v9, v[20:21], off nt
	s_nop 0
	v_addc_co_u32_e32 v23, vcc, 0, v21, vcc
	global_load_dword v18, v[22:23], off nt
	v_add_co_u32_e32 v22, vcc, 0x20000, v20
	s_lshl_b32 s90, s17, 1
	s_nop 0
	v_addc_co_u32_e32 v23, vcc, 0, v21, vcc
	global_load_dword v30, v[22:23], off nt
	v_add_co_u32_e32 v22, vcc, 0x30000, v20
	s_nop 1
	v_addc_co_u32_e32 v23, vcc, 0, v21, vcc
	global_load_dword v31, v[22:23], off nt
	v_add_co_u32_e32 v22, vcc, 0x40000, v20
	s_nop 1
	v_addc_co_u32_e32 v23, vcc, 0, v21, vcc
	global_load_dword v32, v[22:23], off nt
	v_add_co_u32_e32 v22, vcc, 0x50000, v20
	s_nop 1
	v_addc_co_u32_e32 v23, vcc, 0, v21, vcc
	global_load_dword v33, v[22:23], off nt
	v_add_co_u32_e32 v22, vcc, 0x60000, v20
	s_nop 1
	v_addc_co_u32_e32 v23, vcc, 0, v21, vcc
	global_load_dword v34, v[22:23], off nt
	v_add_co_u32_e32 v22, vcc, 0x70000, v20
	s_nop 1
	v_addc_co_u32_e32 v23, vcc, 0, v21, vcc
	global_load_dword v35, v[22:23], off nt
	v_add_co_u32_e32 v22, vcc, 0x80000, v20
	s_nop 1
	v_addc_co_u32_e32 v23, vcc, 0, v21, vcc
	global_load_dword v36, v[22:23], off nt
	v_add_co_u32_e32 v22, vcc, 0x90000, v20
	s_nop 1
	v_addc_co_u32_e32 v23, vcc, 0, v21, vcc
	global_load_dword v37, v[22:23], off nt
	v_add_co_u32_e32 v22, vcc, 0xa0000, v20
	s_nop 1
	v_addc_co_u32_e32 v23, vcc, 0, v21, vcc
	global_load_dword v38, v[22:23], off nt
	v_add_co_u32_e32 v22, vcc, 0xb0000, v20
	s_nop 1
	v_addc_co_u32_e32 v23, vcc, 0, v21, vcc
	global_load_dword v39, v[22:23], off nt
	v_add_co_u32_e32 v22, vcc, 0xc0000, v20
	s_nop 1
	v_addc_co_u32_e32 v23, vcc, 0, v21, vcc
	global_load_dword v40, v[22:23], off nt
	v_add_co_u32_e32 v22, vcc, 0xd0000, v20
	s_nop 1
	v_addc_co_u32_e32 v23, vcc, 0, v21, vcc
	global_load_dword v41, v[22:23], off nt
	v_add_co_u32_e32 v22, vcc, 0xe0000, v20
	s_nop 1
	v_addc_co_u32_e32 v23, vcc, 0, v21, vcc
	global_load_dword v42, v[22:23], off nt
	v_add_co_u32_e32 v22, vcc, 0xf0000, v20
	s_nop 1
	v_addc_co_u32_e32 v23, vcc, 0, v21, vcc
	global_load_dword v43, v[22:23], off nt
	v_add_co_u32_e32 v22, vcc, 0x100000, v20
	s_nop 1
	v_addc_co_u32_e32 v23, vcc, 0, v21, vcc
	global_load_dword v44, v[22:23], off nt
	v_add_co_u32_e32 v22, vcc, 0x110000, v20
	s_nop 1
	v_addc_co_u32_e32 v23, vcc, 0, v21, vcc
	global_load_dword v45, v[22:23], off nt
	v_add_co_u32_e32 v22, vcc, 0x120000, v20
	s_nop 1
	v_addc_co_u32_e32 v23, vcc, 0, v21, vcc
	global_load_dword v46, v[22:23], off nt
	v_add_co_u32_e32 v22, vcc, 0x130000, v20
	s_nop 1
	v_addc_co_u32_e32 v23, vcc, 0, v21, vcc
	global_load_dword v47, v[22:23], off nt
	v_add_co_u32_e32 v22, vcc, 0x140000, v20
	s_nop 1
	v_addc_co_u32_e32 v23, vcc, 0, v21, vcc
	global_load_dword v48, v[22:23], off nt
	v_add_co_u32_e32 v22, vcc, 0x150000, v20
	s_nop 1
	v_addc_co_u32_e32 v23, vcc, 0, v21, vcc
	global_load_dword v49, v[22:23], off nt
	v_add_co_u32_e32 v22, vcc, 0x160000, v20
	s_nop 1
	v_addc_co_u32_e32 v23, vcc, 0, v21, vcc
	global_load_dword v50, v[22:23], off nt
	v_add_co_u32_e32 v22, vcc, 0x170000, v20
	s_nop 1
	v_addc_co_u32_e32 v23, vcc, 0, v21, vcc
	global_load_dword v51, v[22:23], off nt
	v_add_co_u32_e32 v22, vcc, 0x180000, v20
	s_nop 1
	v_addc_co_u32_e32 v23, vcc, 0, v21, vcc
	global_load_dword v52, v[22:23], off nt
	v_add_co_u32_e32 v22, vcc, 0x190000, v20
	s_nop 1
	v_addc_co_u32_e32 v23, vcc, 0, v21, vcc
	global_load_dword v53, v[22:23], off nt
	v_add_co_u32_e32 v22, vcc, 0x1a0000, v20
	s_nop 1
	v_addc_co_u32_e32 v23, vcc, 0, v21, vcc
	global_load_dword v54, v[22:23], off nt
	v_add_co_u32_e32 v22, vcc, 0x1b0000, v20
	s_nop 1
	v_addc_co_u32_e32 v23, vcc, 0, v21, vcc
	global_load_dword v55, v[22:23], off nt
	v_add_co_u32_e32 v22, vcc, 0x1c0000, v20
	s_nop 1
	v_addc_co_u32_e32 v23, vcc, 0, v21, vcc
	global_load_dword v56, v[22:23], off nt
	v_add_co_u32_e32 v22, vcc, 0x1d0000, v20
	s_nop 1
	v_addc_co_u32_e32 v23, vcc, 0, v21, vcc
	global_load_dword v57, v[22:23], off nt
	v_add_co_u32_e32 v22, vcc, 0x1e0000, v20
	s_nop 1
	v_addc_co_u32_e32 v23, vcc, 0, v21, vcc
	v_add_co_u32_e32 v20, vcc, 0x1f0000, v20
	global_load_dword v22, v[22:23], off nt
	s_nop 0
	v_addc_co_u32_e32 v21, vcc, 0, v21, vcc
	global_load_dword v20, v[20:21], off nt
	s_waitcnt vmcnt(0)
	ds_write2_b32 v24, v9, v18 offset1:66
	ds_write2_b32 v24, v30, v31 offset0:132 offset1:198
	v_add_u32_e32 v9, 0x400, v24
	ds_write2_b32 v9, v32, v33 offset0:8 offset1:74
	ds_write2_b32 v9, v34, v35 offset0:140 offset1:206
	v_add_u32_e32 v9, 0x800, v24
	ds_write2_b32 v9, v36, v37 offset0:16 offset1:82
	ds_write2_b32 v9, v38, v39 offset0:148 offset1:214
	v_add_u32_e32 v9, 0xc00, v24
	ds_write2_b32 v9, v40, v41 offset0:24 offset1:90
	ds_write2_b32 v9, v42, v43 offset0:156 offset1:222
	v_add_u32_e32 v9, 0x1000, v24
	ds_write2_b32 v9, v44, v45 offset0:32 offset1:98
	ds_write2_b32 v9, v46, v47 offset0:164 offset1:230
	v_add_u32_e32 v9, 0x1400, v24
	ds_write2_b32 v9, v48, v49 offset0:40 offset1:106
	ds_write2_b32 v9, v50, v51 offset0:172 offset1:238
	v_add_u32_e32 v9, 0x1800, v24
	ds_write2_b32 v9, v52, v53 offset0:48 offset1:114
	ds_write2_b32 v9, v54, v55 offset0:180 offset1:246
	v_add_u32_e32 v9, 0x1c00, v24
	ds_write2_b32 v9, v56, v57 offset0:56 offset1:122
	ds_write2_b32 v9, v22, v20 offset0:188 offset1:254
	s_waitcnt lgkmcnt(0)
	v_and_b32_e32 v70, 3, v146
	v_mul_u32_u24_e32 v70, 0x420, v70
	v_lshrrev_b32_e32 v71, 4, v146
	v_lshl_add_u32 v70, v71, 5, v70
	v_bfe_u32 v71, v146, 2, 2
	v_lshl_add_u32 v70, v71, 2, v70
	s_lshl_b32 s100, s49, 14
	v_add_u32_e32 v70, s100, v70
	v_add_u32_e32 v71, 0x1080, v70
	ds_read2_b32 v[22:23], v70 offset0:33 offset1:37
	ds_read2_b32 v[34:35], v70 offset1:4
	ds_read2_b32 v[36:37], v70 offset0:66 offset1:70
	ds_read2_b32 v[38:39], v70 offset0:99 offset1:103
	ds_read2_b32 v[40:41], v70 offset0:132 offset1:136
	ds_read2_b32 v[42:43], v70 offset0:165 offset1:169
	ds_read2_b32 v[44:45], v70 offset0:198 offset1:202
	ds_read2_b32 v[46:47], v70 offset0:231 offset1:235
	s_waitcnt lgkmcnt(7)
	v_bfe_u32 v18, v22, 16, 1
	s_waitcnt lgkmcnt(6)
	v_bfe_u32 v9, v34, 16, 1
	v_add3_u32 v9, v34, v9, s79
	v_lshrrev_b32_e32 v9, 16, v9
	v_add3_u32 v18, v22, v18, s79
	v_and_or_b32 v30, v18, s80, v9
	s_waitcnt lgkmcnt(5)
	v_bfe_u32 v9, v36, 16, 1
	v_add3_u32 v9, v36, v9, s79
	s_waitcnt lgkmcnt(4)
	v_bfe_u32 v18, v38, 16, 1
	v_lshrrev_b32_e32 v9, 16, v9
	v_add3_u32 v18, v38, v18, s79
	v_and_or_b32 v31, v18, s80, v9
	s_waitcnt lgkmcnt(3)
	v_bfe_u32 v9, v40, 16, 1
	v_add3_u32 v9, v40, v9, s79
	s_waitcnt lgkmcnt(2)
	v_bfe_u32 v18, v42, 16, 1
	v_lshrrev_b32_e32 v9, 16, v9
	v_add3_u32 v18, v42, v18, s79
	v_and_or_b32 v32, v18, s80, v9
	s_waitcnt lgkmcnt(1)
	v_bfe_u32 v9, v44, 16, 1
	v_add3_u32 v9, v44, v9, s79
	s_waitcnt lgkmcnt(0)
	v_bfe_u32 v18, v46, 16, 1
	v_lshrrev_b32_e32 v9, 16, v9
	v_add3_u32 v18, v46, v18, s79
	v_add_u32_e32 v48, s16, v25
	v_and_or_b32 v33, v18, s80, v9
	v_ashrrev_i32_e32 v49, 31, v48
	v_bfe_u32 v9, v35, 16, 1
	v_lshl_add_u64 v[20:21], v[10:11], 0, s[90:91]
	s_lshl_b32 s100, s90, 8
	s_lshr_b32 s101, s16, 8
	s_lshl_b32 s101, s101, 20
	s_add_i32 s100, s100, s101
	s_bfe_u32 s101, s16, 0x10007
	s_lshl_b32 s101, s101, 14
	s_add_i32 s100, s100, s101
	s_bfe_u32 s101, s16, 0x20005
	s_lshl_b32 s101, s101, 12
	s_add_i32 s100, s100, s101
	v_lshrrev_b32_e32 v62, 5, v146
	v_lshlrev_b32_e32 v62, 5, v62
	v_lshlrev_b32_e32 v64, 4, v146
	v_xor_b32_e32 v62, v62, v64
	v_add_u32_e32 v62, s100, v62
	v_mov_b32_e32 v63, v19
	v_sub_u32_e32 v68, 0, v8
	v_ashrrev_i32_e32 v69, 31, v68
	v_lshl_add_u64 v[66:67], v[10:11], 0, v[68:69]
	v_lshl_add_u64 v[68:69], v[66:67], 0, v[62:63]
	v_lshlrev_b64 v[48:49], 12, v[48:49]
	v_add3_u32 v9, v35, v9, s79
	v_bfe_u32 v18, v23, 16, 1
	v_lshl_add_u64 v[48:49], v[20:21], 0, v[48:49]
	v_lshrrev_b32_e32 v9, 16, v9
	v_add3_u32 v18, v23, v18, s79
	global_store_dwordx4 v[68:69], v[30:33], off
	v_add_u32_e32 v22, s16, v27
	v_ashrrev_i32_e32 v23, 31, v22
	v_and_or_b32 v30, v18, s80, v9
	v_bfe_u32 v9, v37, 16, 1
	v_add3_u32 v9, v37, v9, s79
	v_bfe_u32 v18, v39, 16, 1
	v_lshrrev_b32_e32 v9, 16, v9
	v_add3_u32 v18, v39, v18, s79
	v_and_or_b32 v31, v18, s80, v9
	v_bfe_u32 v9, v41, 16, 1
	v_add3_u32 v9, v41, v9, s79
	v_bfe_u32 v18, v43, 16, 1
	v_lshrrev_b32_e32 v9, 16, v9
	v_add3_u32 v18, v43, v18, s79
	v_and_or_b32 v32, v18, s80, v9
	v_bfe_u32 v9, v45, 16, 1
	v_add3_u32 v9, v45, v9, s79
	v_bfe_u32 v18, v47, 16, 1
	v_lshrrev_b32_e32 v9, 16, v9
	v_add3_u32 v18, v47, v18, s79
	v_lshlrev_b64 v[22:23], 12, v[22:23]
	v_and_or_b32 v33, v18, s80, v9
	v_lshl_add_u64 v[22:23], v[20:21], 0, v[22:23]
	global_store_dwordx4 v[68:69], v[30:33], off offset:2048
	ds_read2_b32 v[22:23], v71 offset0:33 offset1:37
	ds_read2_b32 v[34:35], v71 offset1:4
	ds_read2_b32 v[36:37], v71 offset0:66 offset1:70
	ds_read2_b32 v[38:39], v71 offset0:99 offset1:103
	ds_read2_b32 v[40:41], v71 offset0:132 offset1:136
	ds_read2_b32 v[42:43], v71 offset0:165 offset1:169
	ds_read2_b32 v[44:45], v71 offset0:198 offset1:202
	ds_read2_b32 v[46:47], v71 offset0:231 offset1:235
	s_waitcnt lgkmcnt(7)
	v_bfe_u32 v18, v22, 16, 1
	s_waitcnt lgkmcnt(6)
	v_bfe_u32 v9, v34, 16, 1
	v_add3_u32 v9, v34, v9, s79
	v_lshrrev_b32_e32 v9, 16, v9
	v_add3_u32 v18, v22, v18, s79
	v_and_or_b32 v30, v18, s80, v9
	s_waitcnt lgkmcnt(5)
	v_bfe_u32 v9, v36, 16, 1
	v_add3_u32 v9, v36, v9, s79
	s_waitcnt lgkmcnt(4)
	v_bfe_u32 v18, v38, 16, 1
	v_lshrrev_b32_e32 v9, 16, v9
	v_add3_u32 v18, v38, v18, s79
	v_and_or_b32 v31, v18, s80, v9
	s_waitcnt lgkmcnt(3)
	v_bfe_u32 v9, v40, 16, 1
	v_add3_u32 v9, v40, v9, s79
	s_waitcnt lgkmcnt(2)
	v_bfe_u32 v18, v42, 16, 1
	v_lshrrev_b32_e32 v9, 16, v9
	v_add3_u32 v18, v42, v18, s79
	v_and_or_b32 v32, v18, s80, v9
	s_waitcnt lgkmcnt(1)
	v_bfe_u32 v9, v44, 16, 1
	v_add3_u32 v9, v44, v9, s79
	s_waitcnt lgkmcnt(0)
	v_bfe_u32 v18, v46, 16, 1
	v_lshrrev_b32_e32 v9, 16, v9
	v_add3_u32 v18, v46, v18, s79
	v_add_u32_e32 v48, s16, v28
	v_and_or_b32 v33, v18, s80, v9
	v_ashrrev_i32_e32 v49, 31, v48
	v_bfe_u32 v9, v35, 16, 1
	v_lshlrev_b64 v[48:49], 12, v[48:49]
	v_add3_u32 v9, v35, v9, s79
	v_bfe_u32 v18, v23, 16, 1
	v_lshl_add_u64 v[48:49], v[20:21], 0, v[48:49]
	v_lshrrev_b32_e32 v9, 16, v9
	v_add3_u32 v18, v23, v18, s79
	global_store_dwordx4 v[68:69], v[30:33], off offset:1024
	v_add_u32_e32 v22, s16, v29
	v_ashrrev_i32_e32 v23, 31, v22
	v_and_or_b32 v30, v18, s80, v9
	v_bfe_u32 v9, v37, 16, 1
	v_add3_u32 v9, v37, v9, s79
	v_bfe_u32 v18, v39, 16, 1
	v_lshrrev_b32_e32 v9, 16, v9
	v_add3_u32 v18, v39, v18, s79
	v_and_or_b32 v31, v18, s80, v9
	v_bfe_u32 v9, v41, 16, 1
	v_add3_u32 v9, v41, v9, s79
	v_bfe_u32 v18, v43, 16, 1
	v_lshrrev_b32_e32 v9, 16, v9
	v_add3_u32 v18, v43, v18, s79
	v_and_or_b32 v32, v18, s80, v9
	v_bfe_u32 v9, v45, 16, 1
	v_add3_u32 v9, v45, v9, s79
	v_bfe_u32 v18, v47, 16, 1
	v_lshrrev_b32_e32 v9, 16, v9
	v_add3_u32 v18, v47, v18, s79
	v_lshlrev_b64 v[22:23], 12, v[22:23]
	v_and_or_b32 v33, v18, s80, v9
	v_lshl_add_u64 v[20:21], v[20:21], 0, v[22:23]
	global_store_dwordx4 v[68:69], v[30:33], off offset:3072
	s_waitcnt lgkmcnt(0)

.LBB0_330:
	s_andn2_b64 vcc, exec, s[16:17]
	s_cbranch_vccnz .LBB0_332
	s_and_b32 s16, s20, 0x1fc0
	s_addk_i32 s16, 0xed00
	s_lshl_b32 s17, s20, 5
	s_and_b32 s21, s17, 0x7e0
	v_add_u32_e32 v20, s16, v1
	s_lshl_b32 s90, s21, 2
	v_ashrrev_i32_e32 v21, 31, v20
	v_lshl_add_u64 v[22:23], v[12:13], 0, s[90:91]
	v_lshlrev_b64 v[20:21], 13, v[20:21]
	v_lshl_add_u64 v[20:21], v[22:23], 0, v[20:21]
	v_add_co_u32_e32 v22, vcc, 0x4000, v20
	global_load_dword v9, v[20:21], off nt
	s_nop 0
	v_addc_co_u32_e32 v23, vcc, 0, v21, vcc
	global_load_dword v18, v[22:23], off nt
	v_add_co_u32_e32 v22, vcc, 0x8000, v20
	s_mov_b32 s17, 0xc000
	s_nop 0
	v_addc_co_u32_e32 v23, vcc, 0, v21, vcc
	global_load_dword v30, v[22:23], off nt
	v_add_co_u32_e32 v22, vcc, s17, v20
	s_mov_b32 s17, 0x10000
	s_nop 0
	v_addc_co_u32_e32 v23, vcc, 0, v21, vcc
	global_load_dword v31, v[22:23], off nt
	v_add_co_u32_e32 v22, vcc, s17, v20
	s_mov_b32 s17, 0x14000
	s_nop 0
	v_addc_co_u32_e32 v23, vcc, 0, v21, vcc
	global_load_dword v32, v[22:23], off nt
	v_add_co_u32_e32 v22, vcc, s17, v20
	s_mov_b32 s17, 0x18000
	s_nop 0
	v_addc_co_u32_e32 v23, vcc, 0, v21, vcc
	global_load_dword v33, v[22:23], off nt
	v_add_co_u32_e32 v22, vcc, s17, v20
	s_mov_b32 s17, 0x1c000
	s_nop 0
	v_addc_co_u32_e32 v23, vcc, 0, v21, vcc
	global_load_dword v34, v[22:23], off nt
	v_add_co_u32_e32 v22, vcc, s17, v20
	s_mov_b32 s17, 0x20000
	s_nop 0
	v_addc_co_u32_e32 v23, vcc, 0, v21, vcc
	global_load_dword v35, v[22:23], off nt
	v_add_co_u32_e32 v22, vcc, s17, v20
	s_mov_b32 s17, 0x24000
	s_nop 0
	v_addc_co_u32_e32 v23, vcc, 0, v21, vcc
	global_load_dword v36, v[22:23], off nt
	v_add_co_u32_e32 v22, vcc, s17, v20
	s_mov_b32 s17, 0x28000
	s_nop 0
	v_addc_co_u32_e32 v23, vcc, 0, v21, vcc
	global_load_dword v37, v[22:23], off nt
	v_add_co_u32_e32 v22, vcc, s17, v20
	s_mov_b32 s17, 0x2c000
	s_nop 0
	v_addc_co_u32_e32 v23, vcc, 0, v21, vcc
	global_load_dword v38, v[22:23], off nt
	v_add_co_u32_e32 v22, vcc, s17, v20
	s_mov_b32 s17, 0x30000
	s_nop 0
	v_addc_co_u32_e32 v23, vcc, 0, v21, vcc
	global_load_dword v39, v[22:23], off nt
	v_add_co_u32_e32 v22, vcc, s17, v20
	s_mov_b32 s17, 0x34000
	s_nop 0
	v_addc_co_u32_e32 v23, vcc, 0, v21, vcc
	global_load_dword v40, v[22:23], off nt
	v_add_co_u32_e32 v22, vcc, s17, v20
	s_mov_b32 s17, 0x38000
	s_nop 0
	v_addc_co_u32_e32 v23, vcc, 0, v21, vcc
	global_load_dword v41, v[22:23], off nt
	v_add_co_u32_e32 v22, vcc, s17, v20
	s_mov_b32 s17, 0x3c000
	s_nop 0
	v_addc_co_u32_e32 v23, vcc, 0, v21, vcc
	global_load_dword v42, v[22:23], off nt
	v_add_co_u32_e32 v22, vcc, s17, v20
	s_mov_b32 s17, 0x40000
	s_nop 0
	v_addc_co_u32_e32 v23, vcc, 0, v21, vcc
	global_load_dword v43, v[22:23], off nt
	v_add_co_u32_e32 v22, vcc, s17, v20
	s_mov_b32 s17, 0x44000
	s_nop 0
	v_addc_co_u32_e32 v23, vcc, 0, v21, vcc
	global_load_dword v44, v[22:23], off nt
	v_add_co_u32_e32 v22, vcc, s17, v20
	s_mov_b32 s17, 0x48000
	s_nop 0
	v_addc_co_u32_e32 v23, vcc, 0, v21, vcc
	global_load_dword v45, v[22:23], off nt
	v_add_co_u32_e32 v22, vcc, s17, v20
	s_mov_b32 s17, 0x4c000
	s_nop 0
	v_addc_co_u32_e32 v23, vcc, 0, v21, vcc
	global_load_dword v46, v[22:23], off nt
	v_add_co_u32_e32 v22, vcc, s17, v20
	s_mov_b32 s17, 0x50000
	s_nop 0
	v_addc_co_u32_e32 v23, vcc, 0, v21, vcc
	global_load_dword v47, v[22:23], off nt
	v_add_co_u32_e32 v22, vcc, s17, v20
	s_mov_b32 s17, 0x54000
	s_nop 0
	v_addc_co_u32_e32 v23, vcc, 0, v21, vcc
	global_load_dword v48, v[22:23], off nt
	v_add_co_u32_e32 v22, vcc, s17, v20
	s_mov_b32 s17, 0x58000
	s_nop 0
	v_addc_co_u32_e32 v23, vcc, 0, v21, vcc
	global_load_dword v49, v[22:23], off nt
	v_add_co_u32_e32 v22, vcc, s17, v20
	s_mov_b32 s17, 0x5c000
	s_nop 0
	v_addc_co_u32_e32 v23, vcc, 0, v21, vcc
	global_load_dword v50, v[22:23], off nt
	v_add_co_u32_e32 v22, vcc, s17, v20
	s_mov_b32 s17, 0x60000
	s_nop 0
	v_addc_co_u32_e32 v23, vcc, 0, v21, vcc
	global_load_dword v51, v[22:23], off nt
	v_add_co_u32_e32 v22, vcc, s17, v20
	s_mov_b32 s17, 0x64000
	s_nop 0
	v_addc_co_u32_e32 v23, vcc, 0, v21, vcc
	global_load_dword v52, v[22:23], off nt
	v_add_co_u32_e32 v22, vcc, s17, v20
	s_mov_b32 s17, 0x68000
	s_nop 0
	v_addc_co_u32_e32 v23, vcc, 0, v21, vcc
	global_load_dword v53, v[22:23], off nt
	v_add_co_u32_e32 v22, vcc, s17, v20
	s_mov_b32 s17, 0x6c000
	s_nop 0
	v_addc_co_u32_e32 v23, vcc, 0, v21, vcc
	global_load_dword v54, v[22:23], off nt
	v_add_co_u32_e32 v22, vcc, s17, v20
	s_mov_b32 s17, 0x70000
	s_nop 0
	v_addc_co_u32_e32 v23, vcc, 0, v21, vcc
	global_load_dword v55, v[22:23], off nt
	v_add_co_u32_e32 v22, vcc, s17, v20
	s_mov_b32 s17, 0x74000
	s_nop 0
	v_addc_co_u32_e32 v23, vcc, 0, v21, vcc
	global_load_dword v56, v[22:23], off nt
	v_add_co_u32_e32 v22, vcc, s17, v20
	s_mov_b32 s17, 0x78000
	s_nop 0
	v_addc_co_u32_e32 v23, vcc, 0, v21, vcc
	global_load_dword v57, v[22:23], off nt
	v_add_co_u32_e32 v22, vcc, s17, v20
	s_mov_b32 s17, 0x7c000
	s_nop 0
	v_addc_co_u32_e32 v23, vcc, 0, v21, vcc
	v_add_co_u32_e32 v20, vcc, s17, v20
	global_load_dword v22, v[22:23], off nt
	s_nop 0
	v_addc_co_u32_e32 v21, vcc, 0, v21, vcc
	global_load_dword v20, v[20:21], off nt
	s_waitcnt vmcnt(0)
	ds_write2_b32 v24, v9, v18 offset1:66
	ds_write2_b32 v24, v30, v31 offset0:132 offset1:198
	v_add_u32_e32 v9, 0x400, v24
	ds_write2_b32 v9, v32, v33 offset0:8 offset1:74
	ds_write2_b32 v9, v34, v35 offset0:140 offset1:206
	v_add_u32_e32 v9, 0x800, v24
	ds_write2_b32 v9, v36, v37 offset0:16 offset1:82
	ds_write2_b32 v9, v38, v39 offset0:148 offset1:214
	v_add_u32_e32 v9, 0xc00, v24
	ds_write2_b32 v9, v40, v41 offset0:24 offset1:90
	ds_write2_b32 v9, v42, v43 offset0:156 offset1:222
	v_add_u32_e32 v9, 0x1000, v24
	ds_write2_b32 v9, v44, v45 offset0:32 offset1:98
	ds_write2_b32 v9, v46, v47 offset0:164 offset1:230
	v_add_u32_e32 v9, 0x1400, v24
	ds_write2_b32 v9, v48, v49 offset0:40 offset1:106
	ds_write2_b32 v9, v50, v51 offset0:172 offset1:238
	v_add_u32_e32 v9, 0x1800, v24
	ds_write2_b32 v9, v52, v53 offset0:48 offset1:114
	ds_write2_b32 v9, v54, v55 offset0:180 offset1:246
	v_add_u32_e32 v9, 0x1c00, v24
	ds_write2_b32 v9, v56, v57 offset0:56 offset1:122
	ds_write2_b32 v9, v22, v20 offset0:188 offset1:254
	s_waitcnt lgkmcnt(0)
	ds_read2_b32 v[22:23], v26 offset0:33 offset1:41
	ds_read2_b32 v[34:35], v26 offset1:8
	ds_read2_b32 v[36:37], v26 offset0:66 offset1:74
	ds_read2_b32 v[38:39], v26 offset0:99 offset1:107
	ds_read2_b32 v[40:41], v26 offset0:132 offset1:140
	ds_read2_b32 v[42:43], v26 offset0:165 offset1:173
	ds_read2_b32 v[44:45], v26 offset0:198 offset1:206
	ds_read2_b32 v[46:47], v26 offset0:231 offset1:239
	s_waitcnt lgkmcnt(7)
	v_bfe_u32 v18, v22, 16, 1
	s_waitcnt lgkmcnt(6)
	v_bfe_u32 v9, v34, 16, 1
	v_add3_u32 v9, v34, v9, s79
	v_lshrrev_b32_e32 v9, 16, v9
	v_add3_u32 v18, v22, v18, s79
	v_and_or_b32 v30, v18, s80, v9
	s_waitcnt lgkmcnt(5)
	v_bfe_u32 v9, v36, 16, 1
	v_add3_u32 v9, v36, v9, s79
	s_waitcnt lgkmcnt(4)
	v_bfe_u32 v18, v38, 16, 1
	v_lshrrev_b32_e32 v9, 16, v9
	v_add3_u32 v18, v38, v18, s79
	v_and_or_b32 v31, v18, s80, v9
	s_waitcnt lgkmcnt(3)
	v_bfe_u32 v9, v40, 16, 1
	v_add3_u32 v9, v40, v9, s79
	s_waitcnt lgkmcnt(2)
	v_bfe_u32 v18, v42, 16, 1
	v_lshrrev_b32_e32 v9, 16, v9
	v_add3_u32 v18, v42, v18, s79
	v_and_or_b32 v32, v18, s80, v9
	s_waitcnt lgkmcnt(1)
	v_bfe_u32 v9, v44, 16, 1
	v_add3_u32 v9, v44, v9, s79
	s_waitcnt lgkmcnt(0)
	v_bfe_u32 v18, v46, 16, 1
	v_lshrrev_b32_e32 v9, 16, v9
	v_add3_u32 v18, v46, v18, s79
	v_add_u32_e32 v48, s21, v25
	s_mov_b32 s17, s91
	v_and_or_b32 v33, v18, s80, v9
	v_ashrrev_i32_e32 v49, 31, v48
	v_bfe_u32 v9, v35, 16, 1
	v_lshl_add_u64 v[20:21], s[16:17], 1, v[14:15]
	v_lshlrev_b64 v[48:49], 12, v[48:49]
	v_add3_u32 v9, v35, v9, s79
	v_bfe_u32 v18, v23, 16, 1
	v_lshl_add_u64 v[48:49], v[20:21], 0, v[48:49]
	v_lshrrev_b32_e32 v9, 16, v9
	v_add3_u32 v18, v23, v18, s79
	global_store_dwordx4 v[48:49], v[30:33], off
	v_add_u32_e32 v22, s21, v27
	v_ashrrev_i32_e32 v23, 31, v22
	v_and_or_b32 v30, v18, s80, v9
	v_bfe_u32 v9, v37, 16, 1
	v_add3_u32 v9, v37, v9, s79
	v_bfe_u32 v18, v39, 16, 1
	v_lshrrev_b32_e32 v9, 16, v9
	v_add3_u32 v18, v39, v18, s79
	v_and_or_b32 v31, v18, s80, v9
	v_bfe_u32 v9, v41, 16, 1
	v_add3_u32 v9, v41, v9, s79
	v_bfe_u32 v18, v43, 16, 1
	v_lshrrev_b32_e32 v9, 16, v9
	v_add3_u32 v18, v43, v18, s79
	v_and_or_b32 v32, v18, s80, v9
	v_bfe_u32 v9, v45, 16, 1
	v_add3_u32 v9, v45, v9, s79
	v_bfe_u32 v18, v47, 16, 1
	v_lshrrev_b32_e32 v9, 16, v9
	v_add3_u32 v18, v47, v18, s79
	v_lshlrev_b64 v[22:23], 12, v[22:23]
	v_and_or_b32 v33, v18, s80, v9
	v_lshl_add_u64 v[22:23], v[20:21], 0, v[22:23]
	global_store_dwordx4 v[22:23], v[30:33], off
	ds_read2_b32 v[22:23], v26 offset0:49 offset1:57
	ds_read2_b32 v[34:35], v26 offset0:16 offset1:24
	ds_read2_b32 v[36:37], v26 offset0:82 offset1:90
	ds_read2_b32 v[38:39], v26 offset0:115 offset1:123
	ds_read2_b32 v[40:41], v26 offset0:148 offset1:156
	ds_read2_b32 v[42:43], v26 offset0:181 offset1:189
	ds_read2_b32 v[44:45], v26 offset0:214 offset1:222
	ds_read2_b32 v[46:47], v26 offset0:247 offset1:255
	s_waitcnt lgkmcnt(7)
	v_bfe_u32 v18, v22, 16, 1
	s_waitcnt lgkmcnt(6)
	v_bfe_u32 v9, v34, 16, 1
	v_add3_u32 v9, v34, v9, s79
	v_lshrrev_b32_e32 v9, 16, v9
	v_add3_u32 v18, v22, v18, s79
	v_and_or_b32 v30, v18, s80, v9
	s_waitcnt lgkmcnt(5)
	v_bfe_u32 v9, v36, 16, 1
	v_add3_u32 v9, v36, v9, s79
	s_waitcnt lgkmcnt(4)
	v_bfe_u32 v18, v38, 16, 1
	v_lshrrev_b32_e32 v9, 16, v9
	v_add3_u32 v18, v38, v18, s79
	v_and_or_b32 v31, v18, s80, v9
	s_waitcnt lgkmcnt(3)
	v_bfe_u32 v9, v40, 16, 1
	v_add3_u32 v9, v40, v9, s79
	s_waitcnt lgkmcnt(2)
	v_bfe_u32 v18, v42, 16, 1
	v_lshrrev_b32_e32 v9, 16, v9
	v_add3_u32 v18, v42, v18, s79
	v_and_or_b32 v32, v18, s80, v9
	s_waitcnt lgkmcnt(1)
	v_bfe_u32 v9, v44, 16, 1
	v_add3_u32 v9, v44, v9, s79
	s_waitcnt lgkmcnt(0)
	v_bfe_u32 v18, v46, 16, 1
	v_lshrrev_b32_e32 v9, 16, v9
	v_add3_u32 v18, v46, v18, s79
	v_add_u32_e32 v48, s21, v28
	v_and_or_b32 v33, v18, s80, v9
	v_ashrrev_i32_e32 v49, 31, v48
	v_bfe_u32 v9, v35, 16, 1
	v_lshlrev_b64 v[48:49], 12, v[48:49]
	v_add3_u32 v9, v35, v9, s79
	v_bfe_u32 v18, v23, 16, 1
	v_lshl_add_u64 v[48:49], v[20:21], 0, v[48:49]
	v_lshrrev_b32_e32 v9, 16, v9
	v_add3_u32 v18, v23, v18, s79
	global_store_dwordx4 v[48:49], v[30:33], off
	v_add_u32_e32 v22, s21, v29
	v_ashrrev_i32_e32 v23, 31, v22
	v_and_or_b32 v30, v18, s80, v9
	v_bfe_u32 v9, v37, 16, 1
	v_add3_u32 v9, v37, v9, s79
	v_bfe_u32 v18, v39, 16, 1
	v_lshrrev_b32_e32 v9, 16, v9
	v_add3_u32 v18, v39, v18, s79
	v_and_or_b32 v31, v18, s80, v9
	v_bfe_u32 v9, v41, 16, 1
	v_add3_u32 v9, v41, v9, s79
	v_bfe_u32 v18, v43, 16, 1
	v_lshrrev_b32_e32 v9, 16, v9
	v_add3_u32 v18, v43, v18, s79
	v_and_or_b32 v32, v18, s80, v9
	v_bfe_u32 v9, v45, 16, 1
	v_add3_u32 v9, v45, v9, s79
	v_bfe_u32 v18, v47, 16, 1
	v_lshrrev_b32_e32 v9, 16, v9
	v_add3_u32 v18, v47, v18, s79
	v_lshlrev_b64 v[22:23], 12, v[22:23]
	v_and_or_b32 v33, v18, s80, v9
	v_lshl_add_u64 v[20:21], v[20:21], 0, v[22:23]
	global_store_dwordx4 v[20:21], v[30:33], off
	s_waitcnt lgkmcnt(0)

.LBB0_333:
	s_andn2_b64 vcc, exec, s[16:17]
	s_cbranch_vccnz .LBB0_321
	s_mul_hi_i32 s16, s20, 0x6bca1af3
	s_lshr_b32 s17, s16, 31
	s_ashr_i32 s16, s16, 6
	s_add_i32 s16, s16, s17
	s_mul_i32 s17, s16, 0x98
	s_sub_i32 s17, s20, s17
	s_lshl_b32 s20, s17, 5
	s_cmpk_gt_i32 s17, 0x7f
	s_cselect_b32 s17, 8, 0
	s_or_b32 s22, s17, s20
	s_lshl_b32 s16, s16, 6
	s_ashr_i32 s23, s22, 31
	v_add_u32_e32 v9, s16, v1
	v_lshl_add_u64 v[20:21], s[22:23], 2, v[2:3]
	v_mad_i64_i32 v[22:23], s[22:23], v9, s37, v[20:21]
	global_load_dword v18, v[22:23], off nt
	v_add_u32_e32 v22, 2, v9
	v_mad_i64_i32 v[22:23], s[22:23], v22, s37, v[20:21]
	global_load_dword v30, v[22:23], off nt
	v_add_u32_e32 v22, 4, v9
	v_mad_i64_i32 v[22:23], s[22:23], v22, s37, v[20:21]
	global_load_dword v31, v[22:23], off nt
	v_add_u32_e32 v22, 6, v9
	v_mad_i64_i32 v[22:23], s[22:23], v22, s37, v[20:21]
	global_load_dword v32, v[22:23], off nt
	v_add_u32_e32 v22, 8, v9
	v_mad_i64_i32 v[22:23], s[22:23], v22, s37, v[20:21]
	global_load_dword v33, v[22:23], off nt
	v_add_u32_e32 v22, 10, v9
	v_mad_i64_i32 v[22:23], s[22:23], v22, s37, v[20:21]
	global_load_dword v34, v[22:23], off nt
	v_add_u32_e32 v22, 12, v9
	v_mad_i64_i32 v[22:23], s[22:23], v22, s37, v[20:21]
	global_load_dword v35, v[22:23], off nt
	v_add_u32_e32 v22, 14, v9
	v_mad_i64_i32 v[22:23], s[22:23], v22, s37, v[20:21]
	global_load_dword v36, v[22:23], off nt
	v_add_u32_e32 v22, 16, v9
	v_mad_i64_i32 v[22:23], s[22:23], v22, s37, v[20:21]
	global_load_dword v37, v[22:23], off nt
	v_add_u32_e32 v22, 18, v9
	v_mad_i64_i32 v[22:23], s[22:23], v22, s37, v[20:21]
	global_load_dword v38, v[22:23], off nt
	v_add_u32_e32 v22, 20, v9
	v_mad_i64_i32 v[22:23], s[22:23], v22, s37, v[20:21]
	global_load_dword v39, v[22:23], off nt
	v_add_u32_e32 v22, 22, v9
	v_mad_i64_i32 v[22:23], s[22:23], v22, s37, v[20:21]
	global_load_dword v40, v[22:23], off nt
	v_add_u32_e32 v22, 24, v9
	v_mad_i64_i32 v[22:23], s[22:23], v22, s37, v[20:21]
	global_load_dword v41, v[22:23], off nt
	v_add_u32_e32 v22, 26, v9
	v_mad_i64_i32 v[22:23], s[22:23], v22, s37, v[20:21]
	global_load_dword v42, v[22:23], off nt
	v_add_u32_e32 v22, 28, v9
	v_mad_i64_i32 v[22:23], s[22:23], v22, s37, v[20:21]
	global_load_dword v43, v[22:23], off nt
	v_add_u32_e32 v22, 30, v9
	v_mad_i64_i32 v[22:23], s[22:23], v22, s37, v[20:21]
	global_load_dword v44, v[22:23], off nt
	v_add_u32_e32 v22, 32, v9
	v_mad_i64_i32 v[22:23], s[22:23], v22, s37, v[20:21]
	global_load_dword v45, v[22:23], off nt
	v_add_u32_e32 v22, 34, v9
	v_mad_i64_i32 v[22:23], s[22:23], v22, s37, v[20:21]
	global_load_dword v46, v[22:23], off nt
	v_add_u32_e32 v22, 36, v9
	v_mad_i64_i32 v[22:23], s[22:23], v22, s37, v[20:21]
	global_load_dword v47, v[22:23], off nt
	v_add_u32_e32 v22, 38, v9
	v_mad_i64_i32 v[22:23], s[22:23], v22, s37, v[20:21]
	global_load_dword v48, v[22:23], off nt
	v_add_u32_e32 v22, 40, v9
	v_mad_i64_i32 v[22:23], s[22:23], v22, s37, v[20:21]
	global_load_dword v49, v[22:23], off nt
	v_add_u32_e32 v22, 42, v9
	v_mad_i64_i32 v[22:23], s[22:23], v22, s37, v[20:21]
	global_load_dword v50, v[22:23], off nt
	v_add_u32_e32 v22, 44, v9
	v_mad_i64_i32 v[22:23], s[22:23], v22, s37, v[20:21]
	global_load_dword v51, v[22:23], off nt
	v_add_u32_e32 v22, 46, v9
	v_mad_i64_i32 v[22:23], s[22:23], v22, s37, v[20:21]
	global_load_dword v52, v[22:23], off nt
	v_add_u32_e32 v22, 48, v9
	v_mad_i64_i32 v[22:23], s[22:23], v22, s37, v[20:21]
	global_load_dword v53, v[22:23], off nt
	v_add_u32_e32 v22, 50, v9
	v_mad_i64_i32 v[22:23], s[22:23], v22, s37, v[20:21]
	global_load_dword v54, v[22:23], off nt
	v_add_u32_e32 v22, 52, v9
	v_mad_i64_i32 v[22:23], s[22:23], v22, s37, v[20:21]
	global_load_dword v55, v[22:23], off nt
	v_add_u32_e32 v22, 54, v9
	v_mad_i64_i32 v[22:23], s[22:23], v22, s37, v[20:21]
	global_load_dword v56, v[22:23], off nt
	v_add_u32_e32 v22, 56, v9
	v_mad_i64_i32 v[22:23], s[22:23], v22, s37, v[20:21]
	global_load_dword v57, v[22:23], off nt
	v_add_u32_e32 v22, 58, v9
	v_mad_i64_i32 v[22:23], s[22:23], v22, s37, v[20:21]
	global_load_dword v58, v[22:23], off nt
	v_add_u32_e32 v22, 60, v9
	v_add_u32_e32 v9, 62, v9
	v_mad_i64_i32 v[22:23], s[22:23], v22, s37, v[20:21]
	v_mad_i64_i32 v[20:21], s[22:23], v9, s37, v[20:21]
	global_load_dword v22, v[22:23], off nt
	s_ashr_i32 s17, s16, 31
	global_load_dword v9, v[20:21], off nt
	s_waitcnt vmcnt(0)
	ds_write2_b32 v24, v18, v30 offset1:66
	ds_write2_b32 v24, v31, v32 offset0:132 offset1:198
	v_add_u32_e32 v18, 0x400, v24
	ds_write2_b32 v18, v33, v34 offset0:8 offset1:74
	ds_write2_b32 v18, v35, v36 offset0:140 offset1:206
	v_add_u32_e32 v18, 0x800, v24
	ds_write2_b32 v18, v37, v38 offset0:16 offset1:82
	ds_write2_b32 v18, v39, v40 offset0:148 offset1:214
	v_add_u32_e32 v18, 0xc00, v24
	ds_write2_b32 v18, v41, v42 offset0:24 offset1:90
	ds_write2_b32 v18, v43, v44 offset0:156 offset1:222
	v_add_u32_e32 v18, 0x1000, v24
	ds_write2_b32 v18, v45, v46 offset0:32 offset1:98
	ds_write2_b32 v18, v47, v48 offset0:164 offset1:230
	v_add_u32_e32 v18, 0x1400, v24
	ds_write2_b32 v18, v49, v50 offset0:40 offset1:106
	ds_write2_b32 v18, v51, v52 offset0:172 offset1:238
	v_add_u32_e32 v18, 0x1800, v24
	ds_write2_b32 v18, v53, v54 offset0:48 offset1:114
	ds_write2_b32 v18, v55, v56 offset0:180 offset1:246
	v_add_u32_e32 v18, 0x1c00, v24
	ds_write2_b32 v18, v57, v58 offset0:56 offset1:122
	ds_write2_b32 v18, v22, v9 offset0:188 offset1:254
	s_waitcnt lgkmcnt(0)
	ds_read2_b32 v[22:23], v26 offset0:33 offset1:41
	ds_read2_b32 v[34:35], v26 offset1:8
	ds_read2_b32 v[36:37], v26 offset0:66 offset1:74
	ds_read2_b32 v[38:39], v26 offset0:99 offset1:107
	ds_read2_b32 v[40:41], v26 offset0:132 offset1:140
	ds_read2_b32 v[42:43], v26 offset0:165 offset1:173
	ds_read2_b32 v[44:45], v26 offset0:198 offset1:206
	ds_read2_b32 v[46:47], v26 offset0:231 offset1:239
	s_waitcnt lgkmcnt(7)
	v_bfe_u32 v18, v22, 16, 1
	s_waitcnt lgkmcnt(6)
	v_bfe_u32 v9, v34, 16, 1
	v_add3_u32 v9, v34, v9, s79
	v_lshrrev_b32_e32 v9, 16, v9
	v_add3_u32 v18, v22, v18, s79
	v_and_or_b32 v30, v18, s80, v9
	s_waitcnt lgkmcnt(5)
	v_bfe_u32 v9, v36, 16, 1
	v_add3_u32 v9, v36, v9, s79
	s_waitcnt lgkmcnt(4)
	v_bfe_u32 v18, v38, 16, 1
	v_lshrrev_b32_e32 v9, 16, v9
	v_add3_u32 v18, v38, v18, s79
	v_and_or_b32 v31, v18, s80, v9
	s_waitcnt lgkmcnt(3)
	v_bfe_u32 v9, v40, 16, 1
	v_add3_u32 v9, v40, v9, s79
	s_waitcnt lgkmcnt(2)
	v_bfe_u32 v18, v42, 16, 1
	v_lshrrev_b32_e32 v9, 16, v9
	v_add3_u32 v18, v42, v18, s79
	v_and_or_b32 v32, v18, s80, v9
	s_waitcnt lgkmcnt(1)
	v_bfe_u32 v9, v44, 16, 1
	v_add3_u32 v9, v44, v9, s79
	s_waitcnt lgkmcnt(0)
	v_bfe_u32 v18, v46, 16, 1
	v_lshrrev_b32_e32 v9, 16, v9
	v_add3_u32 v18, v46, v18, s79
	v_add_u32_e32 v48, s20, v25
	v_and_or_b32 v33, v18, s80, v9
	v_ashrrev_i32_e32 v49, 31, v48
	v_bfe_u32 v9, v35, 16, 1
	v_lshl_add_u64 v[20:21], s[16:17], 1, v[16:17]
	v_lshlrev_b64 v[48:49], 12, v[48:49]
	v_add3_u32 v9, v35, v9, s79
	v_bfe_u32 v18, v23, 16, 1
	v_lshl_add_u64 v[48:49], v[20:21], 0, v[48:49]
	v_lshrrev_b32_e32 v9, 16, v9
	v_add3_u32 v18, v23, v18, s79
	global_store_dwordx4 v[48:49], v[30:33], off
	v_add_u32_e32 v22, s20, v27
	v_ashrrev_i32_e32 v23, 31, v22
	v_and_or_b32 v30, v18, s80, v9
	v_bfe_u32 v9, v37, 16, 1
	v_add3_u32 v9, v37, v9, s79
	v_bfe_u32 v18, v39, 16, 1
	v_lshrrev_b32_e32 v9, 16, v9
	v_add3_u32 v18, v39, v18, s79
	v_and_or_b32 v31, v18, s80, v9
	v_bfe_u32 v9, v41, 16, 1
	v_add3_u32 v9, v41, v9, s79
	v_bfe_u32 v18, v43, 16, 1
	v_lshrrev_b32_e32 v9, 16, v9
	v_add3_u32 v18, v43, v18, s79
	v_and_or_b32 v32, v18, s80, v9
	v_bfe_u32 v9, v45, 16, 1
	v_add3_u32 v9, v45, v9, s79
	v_bfe_u32 v18, v47, 16, 1
	v_lshrrev_b32_e32 v9, 16, v9
	v_add3_u32 v18, v47, v18, s79
	v_lshlrev_b64 v[22:23], 12, v[22:23]
	v_and_or_b32 v33, v18, s80, v9
	v_lshl_add_u64 v[22:23], v[20:21], 0, v[22:23]
	global_store_dwordx4 v[22:23], v[30:33], off
	ds_read2_b32 v[22:23], v26 offset0:49 offset1:57
	ds_read2_b32 v[34:35], v26 offset0:16 offset1:24
	ds_read2_b32 v[36:37], v26 offset0:82 offset1:90
	ds_read2_b32 v[38:39], v26 offset0:115 offset1:123
	ds_read2_b32 v[40:41], v26 offset0:148 offset1:156
	ds_read2_b32 v[42:43], v26 offset0:181 offset1:189
	ds_read2_b32 v[44:45], v26 offset0:214 offset1:222
	ds_read2_b32 v[46:47], v26 offset0:247 offset1:255
	s_waitcnt lgkmcnt(7)
	v_bfe_u32 v18, v22, 16, 1
	s_waitcnt lgkmcnt(6)
	v_bfe_u32 v9, v34, 16, 1
	v_add3_u32 v9, v34, v9, s79
	v_lshrrev_b32_e32 v9, 16, v9
	v_add3_u32 v18, v22, v18, s79
	v_and_or_b32 v30, v18, s80, v9
	s_waitcnt lgkmcnt(5)
	v_bfe_u32 v9, v36, 16, 1
	v_add3_u32 v9, v36, v9, s79
	s_waitcnt lgkmcnt(4)
	v_bfe_u32 v18, v38, 16, 1
	v_lshrrev_b32_e32 v9, 16, v9
	v_add3_u32 v18, v38, v18, s79
	v_and_or_b32 v31, v18, s80, v9
	s_waitcnt lgkmcnt(3)
	v_bfe_u32 v9, v40, 16, 1
	v_add3_u32 v9, v40, v9, s79
	s_waitcnt lgkmcnt(2)
	v_bfe_u32 v18, v42, 16, 1
	v_lshrrev_b32_e32 v9, 16, v9
	v_add3_u32 v18, v42, v18, s79
	v_and_or_b32 v32, v18, s80, v9
	s_waitcnt lgkmcnt(1)
	v_bfe_u32 v9, v44, 16, 1
	v_add3_u32 v9, v44, v9, s79
	s_waitcnt lgkmcnt(0)
	v_bfe_u32 v18, v46, 16, 1
	v_lshrrev_b32_e32 v9, 16, v9
	v_add3_u32 v18, v46, v18, s79
	v_add_u32_e32 v48, s20, v28
	v_and_or_b32 v33, v18, s80, v9
	v_ashrrev_i32_e32 v49, 31, v48
	v_bfe_u32 v9, v35, 16, 1
	v_lshlrev_b64 v[48:49], 12, v[48:49]
	v_add3_u32 v9, v35, v9, s79
	v_bfe_u32 v18, v23, 16, 1
	v_lshl_add_u64 v[48:49], v[20:21], 0, v[48:49]
	v_lshrrev_b32_e32 v9, 16, v9
	v_add3_u32 v18, v23, v18, s79
	global_store_dwordx4 v[48:49], v[30:33], off
	v_add_u32_e32 v22, s20, v29
	v_ashrrev_i32_e32 v23, 31, v22
	v_and_or_b32 v30, v18, s80, v9
	v_bfe_u32 v9, v37, 16, 1
	v_add3_u32 v9, v37, v9, s79
	v_bfe_u32 v18, v39, 16, 1
	v_lshrrev_b32_e32 v9, 16, v9
	v_add3_u32 v18, v39, v18, s79
	v_and_or_b32 v31, v18, s80, v9
	v_bfe_u32 v9, v41, 16, 1
	v_add3_u32 v9, v41, v9, s79
	v_bfe_u32 v18, v43, 16, 1
	v_lshrrev_b32_e32 v9, 16, v9
	v_add3_u32 v18, v43, v18, s79
	v_and_or_b32 v32, v18, s80, v9
	v_bfe_u32 v9, v45, 16, 1
	v_add3_u32 v9, v45, v9, s79
	v_bfe_u32 v18, v47, 16, 1
	v_lshrrev_b32_e32 v9, 16, v9
	v_add3_u32 v18, v47, v18, s79
	v_lshlrev_b64 v[22:23], 12, v[22:23]
	v_and_or_b32 v33, v18, s80, v9
	v_lshl_add_u64 v[20:21], v[20:21], 0, v[22:23]
	global_store_dwordx4 v[20:21], v[30:33], off
	s_waitcnt lgkmcnt(0)
	s_branch .LBB0_321

.LBB0_1776:
	s_add_i32 s13, s12, s10
	s_cmpk_gt_i32 s13, 0x5aff
	s_cbranch_scc1 .LBB0_1775
	s_cmpk_gt_i32 s13, 0x12ff
	s_mov_b64 s[10:11], -1
	s_cbranch_scc0 .LBB0_1787
	s_cmpk_gt_u32 s13, 0x1aff
	s_cbranch_scc0 .LBB0_1784
	s_cmpk_gt_u32 s13, 0x3aff
	s_cbranch_scc0 .LBB0_1781
	s_and_b32 s10, s13, 0x7fffffc0
	s_addk_i32 s10, 0xc500
	s_lshl_b32 s11, s13, 5
	s_and_b32 s14, s11, 0x7e0
	v_add_u32_e32 v24, s10, v1
	s_lshl_b32 s90, s14, 2
	v_ashrrev_i32_e32 v25, 31, v24
	v_lshl_add_u64 v[32:33], v[6:7], 0, s[90:91]
	v_lshlrev_b64 v[24:25], 13, v[24:25]
	v_lshl_add_u64 v[24:25], v[32:33], 0, v[24:25]
	v_add_co_u32_e32 v32, vcc, 0x4000, v24
	global_load_dword v5, v[24:25], off nt
	s_nop 0
	v_addc_co_u32_e32 v33, vcc, 0, v25, vcc
	global_load_dword v11, v[32:33], off nt
	v_add_co_u32_e32 v32, vcc, 0x8000, v24
	s_mov_b32 s11, 0xc000
	s_nop 0
	v_addc_co_u32_e32 v33, vcc, 0, v25, vcc
	global_load_dword v18, v[32:33], off nt
	v_add_co_u32_e32 v32, vcc, s11, v24
	s_mov_b32 s11, 0x10000
	s_nop 0
	v_addc_co_u32_e32 v33, vcc, 0, v25, vcc
	global_load_dword v31, v[32:33], off nt
	v_add_co_u32_e32 v32, vcc, s11, v24
	s_mov_b32 s11, 0x14000
	s_nop 0
	v_addc_co_u32_e32 v33, vcc, 0, v25, vcc
	global_load_dword v34, v[32:33], off nt
	v_add_co_u32_e32 v32, vcc, s11, v24
	s_mov_b32 s11, 0x18000
	s_nop 0
	v_addc_co_u32_e32 v33, vcc, 0, v25, vcc
	global_load_dword v35, v[32:33], off nt
	v_add_co_u32_e32 v32, vcc, s11, v24
	s_mov_b32 s11, 0x1c000
	s_nop 0
	v_addc_co_u32_e32 v33, vcc, 0, v25, vcc
	global_load_dword v36, v[32:33], off nt
	v_add_co_u32_e32 v32, vcc, s11, v24
	s_mov_b32 s11, 0x20000
	s_nop 0
	v_addc_co_u32_e32 v33, vcc, 0, v25, vcc
	global_load_dword v37, v[32:33], off nt
	v_add_co_u32_e32 v32, vcc, s11, v24
	s_mov_b32 s11, 0x58000
	s_nop 0
	v_addc_co_u32_e32 v33, vcc, 0, v25, vcc
	global_load_dword v38, v[32:33], off nt
	v_add_co_u32_e32 v32, vcc, s19, v24
	s_lshr_b32 s90, s10, 6
	s_nop 0
	v_addc_co_u32_e32 v33, vcc, 0, v25, vcc
	global_load_dword v39, v[32:33], off nt
	v_add_co_u32_e32 v32, vcc, s20, v24
	s_nop 1
	v_addc_co_u32_e32 v33, vcc, 0, v25, vcc
	global_load_dword v40, v[32:33], off nt
	v_add_co_u32_e32 v32, vcc, s21, v24
	s_nop 1
	v_addc_co_u32_e32 v33, vcc, 0, v25, vcc
	global_load_dword v41, v[32:33], off nt
	v_add_co_u32_e32 v32, vcc, s22, v24
	s_nop 1
	v_addc_co_u32_e32 v33, vcc, 0, v25, vcc
	global_load_dword v42, v[32:33], off nt
	v_add_co_u32_e32 v32, vcc, s23, v24
	s_nop 1
	v_addc_co_u32_e32 v33, vcc, 0, v25, vcc
	global_load_dword v43, v[32:33], off nt
	v_add_co_u32_e32 v32, vcc, s24, v24
	s_nop 1
	v_addc_co_u32_e32 v33, vcc, 0, v25, vcc
	global_load_dword v44, v[32:33], off nt
	v_add_co_u32_e32 v32, vcc, s25, v24
	s_nop 1
	v_addc_co_u32_e32 v33, vcc, 0, v25, vcc
	global_load_dword v45, v[32:33], off nt
	v_add_co_u32_e32 v32, vcc, s26, v24
	s_nop 1
	v_addc_co_u32_e32 v33, vcc, 0, v25, vcc
	global_load_dword v46, v[32:33], off nt
	v_add_co_u32_e32 v32, vcc, s27, v24
	s_nop 1
	v_addc_co_u32_e32 v33, vcc, 0, v25, vcc
	global_load_dword v47, v[32:33], off nt
	v_add_co_u32_e32 v32, vcc, s43, v24
	s_nop 1
	v_addc_co_u32_e32 v33, vcc, 0, v25, vcc
	global_load_dword v48, v[32:33], off nt
	v_add_co_u32_e32 v32, vcc, s44, v24
	s_nop 1
	v_addc_co_u32_e32 v33, vcc, 0, v25, vcc
	global_load_dword v49, v[32:33], off nt
	v_add_co_u32_e32 v32, vcc, s45, v24
	s_nop 1
	v_addc_co_u32_e32 v33, vcc, 0, v25, vcc
	global_load_dword v50, v[32:33], off nt
	v_add_co_u32_e32 v32, vcc, s46, v24
	s_nop 1
	v_addc_co_u32_e32 v33, vcc, 0, v25, vcc
	global_load_dword v51, v[32:33], off nt
	v_add_co_u32_e32 v32, vcc, s11, v24
	s_mov_b32 s11, 0x5c000
	s_nop 0
	v_addc_co_u32_e32 v33, vcc, 0, v25, vcc
	global_load_dword v52, v[32:33], off nt
	v_add_co_u32_e32 v32, vcc, s11, v24
	s_mov_b32 s11, 0x60000
	s_nop 0
	v_addc_co_u32_e32 v33, vcc, 0, v25, vcc
	global_load_dword v53, v[32:33], off nt
	v_add_co_u32_e32 v32, vcc, s11, v24
	s_mov_b32 s11, 0x64000
	s_nop 0
	v_addc_co_u32_e32 v33, vcc, 0, v25, vcc
	global_load_dword v54, v[32:33], off nt
	v_add_co_u32_e32 v32, vcc, s11, v24
	s_mov_b32 s11, 0x68000
	s_nop 0
	v_addc_co_u32_e32 v33, vcc, 0, v25, vcc
	global_load_dword v55, v[32:33], off nt
	v_add_co_u32_e32 v32, vcc, s11, v24
	s_mov_b32 s11, 0x6c000
	s_nop 0
	v_addc_co_u32_e32 v33, vcc, 0, v25, vcc
	global_load_dword v56, v[32:33], off nt
	v_add_co_u32_e32 v32, vcc, s11, v24
	s_mov_b32 s11, 0x70000
	s_nop 0
	v_addc_co_u32_e32 v33, vcc, 0, v25, vcc
	global_load_dword v57, v[32:33], off nt
	v_add_co_u32_e32 v32, vcc, s11, v24
	s_mov_b32 s11, 0x74000
	s_nop 0
	v_addc_co_u32_e32 v33, vcc, 0, v25, vcc
	global_load_dword v58, v[32:33], off nt
	v_add_co_u32_e32 v32, vcc, s11, v24
	s_mov_b32 s11, 0x78000
	s_nop 0
	v_addc_co_u32_e32 v33, vcc, 0, v25, vcc
	global_load_dword v59, v[32:33], off nt
	v_add_co_u32_e32 v32, vcc, s11, v24
	s_mov_b32 s11, 0x7c000
	s_nop 0
	v_addc_co_u32_e32 v33, vcc, 0, v25, vcc
	v_add_co_u32_e32 v24, vcc, s11, v24
	global_load_dword v32, v[32:33], off nt
	s_nop 0
	v_addc_co_u32_e32 v25, vcc, 0, v25, vcc
	global_load_dword v24, v[24:25], off nt
	s_waitcnt vmcnt(0)
	ds_write2_b32 v3, v5, v11 offset1:66
	ds_write2_b32 v3, v18, v31 offset0:132 offset1:198
	v_add_u32_e32 v5, 0x400, v3
	ds_write2_b32 v5, v34, v35 offset0:8 offset1:74
	ds_write2_b32 v5, v36, v37 offset0:140 offset1:206
	v_add_u32_e32 v5, 0x800, v3
	ds_write2_b32 v5, v38, v39 offset0:16 offset1:82
	ds_write2_b32 v5, v40, v41 offset0:148 offset1:214
	v_add_u32_e32 v5, 0xc00, v3
	ds_write2_b32 v5, v42, v43 offset0:24 offset1:90
	ds_write2_b32 v5, v44, v45 offset0:156 offset1:222
	v_add_u32_e32 v5, 0x1000, v3
	ds_write2_b32 v5, v46, v47 offset0:32 offset1:98
	ds_write2_b32 v5, v48, v49 offset0:164 offset1:230
	v_add_u32_e32 v5, 0x1400, v3
	ds_write2_b32 v5, v50, v51 offset0:40 offset1:106
	ds_write2_b32 v5, v52, v53 offset0:172 offset1:238
	v_add_u32_e32 v5, 0x1800, v3
	ds_write2_b32 v5, v54, v55 offset0:48 offset1:114
	ds_write2_b32 v5, v56, v57 offset0:180 offset1:246
	v_add_u32_e32 v5, 0x1c00, v3
	ds_write2_b32 v5, v58, v59 offset0:56 offset1:122
	ds_write2_b32 v5, v32, v24 offset0:188 offset1:254
	s_waitcnt lgkmcnt(0)
	v_and_b32_e32 v70, 3, v146
	v_mul_u32_u24_e32 v70, 0x420, v70
	v_lshrrev_b32_e32 v71, 4, v146
	v_lshl_add_u32 v70, v71, 5, v70
	v_bfe_u32 v71, v146, 2, 2
	v_lshl_add_u32 v70, v71, 2, v70
	s_lshl_b32 s100, s42, 14
	v_add_u32_e32 v70, s100, v70
	v_add_u32_e32 v71, 0x1080, v70
	ds_read2_b32 v[24:25], v70 offset0:33 offset1:37
	ds_read2_b32 v[36:37], v70 offset1:4
	ds_read2_b32 v[38:39], v70 offset0:66 offset1:70
	ds_read2_b32 v[40:41], v70 offset0:99 offset1:103
	ds_read2_b32 v[42:43], v70 offset0:132 offset1:136
	ds_read2_b32 v[44:45], v70 offset0:165 offset1:169
	ds_read2_b32 v[46:47], v70 offset0:198 offset1:202
	ds_read2_b32 v[48:49], v70 offset0:231 offset1:235
	s_waitcnt lgkmcnt(7)
	v_bfe_u32 v11, v24, 16, 1
	s_waitcnt lgkmcnt(6)
	v_bfe_u32 v5, v36, 16, 1
	v_add3_u32 v5, v36, v5, s79
	v_lshrrev_b32_e32 v5, 16, v5
	v_add3_u32 v11, v24, v11, s79
	v_and_or_b32 v32, v11, s80, v5
	s_waitcnt lgkmcnt(5)
	v_bfe_u32 v5, v38, 16, 1
	v_add3_u32 v5, v38, v5, s79
	s_waitcnt lgkmcnt(4)
	v_bfe_u32 v11, v40, 16, 1
	v_lshrrev_b32_e32 v5, 16, v5
	v_add3_u32 v11, v40, v11, s79
	v_and_or_b32 v33, v11, s80, v5
	s_waitcnt lgkmcnt(3)
	v_bfe_u32 v5, v42, 16, 1
	v_add3_u32 v5, v42, v5, s79
	s_waitcnt lgkmcnt(2)
	v_bfe_u32 v11, v44, 16, 1
	v_lshrrev_b32_e32 v5, 16, v5
	v_add3_u32 v11, v44, v11, s79
	v_and_or_b32 v34, v11, s80, v5
	s_waitcnt lgkmcnt(1)
	v_bfe_u32 v5, v46, 16, 1
	v_add3_u32 v5, v46, v5, s79
	s_waitcnt lgkmcnt(0)
	v_bfe_u32 v11, v48, 16, 1
	v_lshrrev_b32_e32 v5, 16, v5
	v_add3_u32 v11, v48, v11, s79
	v_and_or_b32 v35, v11, s80, v5
	v_add_u32_e32 v5, s14, v26
	v_ashrrev_i32_e32 v50, 8, v5
	v_ashrrev_i32_e32 v51, 31, v50
	v_lshlrev_b64 v[50:51], 22, v[50:51]
	s_lshl_b64 s[10:11], s[90:91], 15
	s_lshr_b32 s100, s14, 8
	s_lshl_b32 s100, s100, 22
	s_bfe_u32 s101, s14, 0x10007
	s_lshl_b32 s101, s101, 14
	s_add_i32 s100, s100, s101
	s_bfe_u32 s101, s14, 0x20005
	s_lshl_b32 s101, s101, 12
	s_add_i32 s100, s100, s101
	v_lshrrev_b32_e32 v62, 5, v146
	v_lshlrev_b32_e32 v62, 5, v62
	v_lshlrev_b32_e32 v64, 4, v146
	v_xor_b32_e32 v62, v62, v64
	v_add_u32_e32 v62, s100, v62
	v_mov_b32_e32 v63, v19
	v_lshl_add_u64 v[68:69], s[0:1], 0, v[62:63]
	v_lshl_add_u64 v[68:69], v[68:69], 0, s[10:11]
	v_lshl_add_u64 v[50:51], s[0:1], 0, v[50:51]
	v_lshlrev_b32_e32 v5, 7, v5
	v_lshl_add_u64 v[50:51], v[50:51], 0, s[10:11]
	v_and_b32_e32 v18, 0x7f80, v5
	v_bfe_u32 v5, v37, 16, 1
	v_lshl_add_u64 v[50:51], v[50:51], 0, v[18:19]
	v_mov_b32_e32 v11, v19
	v_add3_u32 v5, v37, v5, s79
	v_bfe_u32 v18, v25, 16, 1
	v_lshl_add_u64 v[50:51], v[50:51], 0, v[10:11]
	v_lshrrev_b32_e32 v5, 16, v5
	v_add3_u32 v18, v25, v18, s79
	global_store_dwordx4 v[68:69], v[32:35], off
	s_nop 1
	v_and_or_b32 v32, v18, s80, v5
	v_bfe_u32 v5, v39, 16, 1
	v_add3_u32 v5, v39, v5, s79
	v_bfe_u32 v18, v41, 16, 1
	v_lshrrev_b32_e32 v5, 16, v5
	v_add3_u32 v18, v41, v18, s79
	v_and_or_b32 v33, v18, s80, v5
	v_bfe_u32 v5, v43, 16, 1
	v_add3_u32 v5, v43, v5, s79
	v_bfe_u32 v18, v45, 16, 1
	v_lshrrev_b32_e32 v5, 16, v5
	v_add3_u32 v18, v45, v18, s79
	v_and_or_b32 v34, v18, s80, v5
	v_bfe_u32 v5, v47, 16, 1
	v_add3_u32 v5, v47, v5, s79
	v_bfe_u32 v18, v49, 16, 1
	v_lshrrev_b32_e32 v5, 16, v5
	v_add3_u32 v18, v49, v18, s79
	v_and_or_b32 v35, v18, s80, v5
	v_add_u32_e32 v5, s14, v28
	v_ashrrev_i32_e32 v24, 8, v5
	v_ashrrev_i32_e32 v25, 31, v24
	v_lshlrev_b64 v[24:25], 22, v[24:25]
	v_lshl_add_u64 v[24:25], s[0:1], 0, v[24:25]
	v_lshlrev_b32_e32 v5, 7, v5
	v_lshl_add_u64 v[24:25], v[24:25], 0, s[10:11]
	v_and_b32_e32 v18, 0x7f80, v5
	v_lshl_add_u64 v[24:25], v[24:25], 0, v[18:19]
	v_lshl_add_u64 v[24:25], v[24:25], 0, v[10:11]
	global_store_dwordx4 v[68:69], v[32:35], off offset:2048
	ds_read2_b32 v[24:25], v71 offset1:4
	ds_read2_b32 v[36:37], v71 offset0:33 offset1:37
	ds_read2_b32 v[38:39], v71 offset0:66 offset1:70
	ds_read2_b32 v[40:41], v71 offset0:99 offset1:103
	ds_read2_b32 v[42:43], v71 offset0:132 offset1:136
	ds_read2_b32 v[44:45], v71 offset0:165 offset1:169
	ds_read2_b32 v[46:47], v71 offset0:198 offset1:202
	ds_read2_b32 v[48:49], v71 offset0:231 offset1:235
	s_waitcnt lgkmcnt(7)
	v_bfe_u32 v5, v24, 16, 1
	v_add3_u32 v5, v24, v5, s79
	s_waitcnt lgkmcnt(6)
	v_bfe_u32 v18, v36, 16, 1
	v_lshrrev_b32_e32 v5, 16, v5
	v_add3_u32 v18, v36, v18, s79
	v_and_or_b32 v32, v18, s80, v5
	s_waitcnt lgkmcnt(5)
	v_bfe_u32 v5, v38, 16, 1
	v_add3_u32 v5, v38, v5, s79
	s_waitcnt lgkmcnt(4)
	v_bfe_u32 v18, v40, 16, 1
	v_lshrrev_b32_e32 v5, 16, v5
	v_add3_u32 v18, v40, v18, s79
	v_and_or_b32 v33, v18, s80, v5
	s_waitcnt lgkmcnt(3)
	v_bfe_u32 v5, v42, 16, 1
	v_add3_u32 v5, v42, v5, s79
	s_waitcnt lgkmcnt(2)
	v_bfe_u32 v18, v44, 16, 1
	v_lshrrev_b32_e32 v5, 16, v5
	v_add3_u32 v18, v44, v18, s79
	v_and_or_b32 v34, v18, s80, v5
	s_waitcnt lgkmcnt(1)
	v_bfe_u32 v5, v46, 16, 1
	v_add3_u32 v5, v46, v5, s79
	s_waitcnt lgkmcnt(0)
	v_bfe_u32 v18, v48, 16, 1
	v_lshrrev_b32_e32 v5, 16, v5
	v_add3_u32 v18, v48, v18, s79
	v_and_or_b32 v35, v18, s80, v5
	v_add_u32_e32 v5, s14, v29
	v_ashrrev_i32_e32 v50, 8, v5
	v_ashrrev_i32_e32 v51, 31, v50
	v_lshlrev_b64 v[50:51], 22, v[50:51]
	v_lshl_add_u64 v[50:51], s[0:1], 0, v[50:51]
	v_lshlrev_b32_e32 v5, 7, v5
	v_lshl_add_u64 v[50:51], v[50:51], 0, s[10:11]
	v_and_b32_e32 v18, 0x7f80, v5
	v_bfe_u32 v5, v25, 16, 1
	v_lshl_add_u64 v[50:51], v[50:51], 0, v[18:19]
	v_add3_u32 v5, v25, v5, s79
	v_bfe_u32 v18, v37, 16, 1
	v_lshl_add_u64 v[50:51], v[50:51], 0, v[10:11]
	v_lshrrev_b32_e32 v5, 16, v5
	v_add3_u32 v18, v37, v18, s79
	global_store_dwordx4 v[68:69], v[32:35], off offset:1024
	s_nop 1
	v_and_or_b32 v32, v18, s80, v5
	v_bfe_u32 v5, v39, 16, 1
	v_add3_u32 v5, v39, v5, s79
	v_bfe_u32 v18, v41, 16, 1
	v_lshrrev_b32_e32 v5, 16, v5
	v_add3_u32 v18, v41, v18, s79
	v_and_or_b32 v33, v18, s80, v5
	v_bfe_u32 v5, v43, 16, 1
	v_add3_u32 v5, v43, v5, s79
	v_bfe_u32 v18, v45, 16, 1
	v_lshrrev_b32_e32 v5, 16, v5
	v_add3_u32 v18, v45, v18, s79
	v_and_or_b32 v34, v18, s80, v5
	v_bfe_u32 v5, v47, 16, 1
	v_add3_u32 v5, v47, v5, s79
	v_bfe_u32 v18, v49, 16, 1
	v_lshrrev_b32_e32 v5, 16, v5
	v_add3_u32 v18, v49, v18, s79
	v_and_or_b32 v35, v18, s80, v5
	v_add_u32_e32 v5, s14, v30
	v_ashrrev_i32_e32 v24, 8, v5
	v_ashrrev_i32_e32 v25, 31, v24
	v_lshlrev_b64 v[24:25], 22, v[24:25]
	v_lshl_add_u64 v[24:25], s[0:1], 0, v[24:25]
	v_lshlrev_b32_e32 v5, 7, v5
	v_lshl_add_u64 v[24:25], v[24:25], 0, s[10:11]
	v_and_b32_e32 v18, 0x7f80, v5
	v_lshl_add_u64 v[24:25], v[24:25], 0, v[18:19]
	v_lshl_add_u64 v[24:25], v[24:25], 0, v[10:11]
	global_store_dwordx4 v[68:69], v[32:35], off offset:3072
	s_waitcnt lgkmcnt(0)
	s_mov_b64 s[10:11], 0
.LBB0_1781:
	s_andn2_b64 vcc, exec, s[10:11]
	s_cbranch_vccnz .LBB0_1783
	s_add_i32 s10, s13, 0xffffe500
	s_lshr_b32 s10, s10, 2
	s_and_b32 s11, s10, 0x3fffffc0
	s_lshl_b32 s10, s13, 5
	s_and_b32 s10, s10, 0x1fe0
	v_add_u32_e32 v24, s11, v1
	s_lshl_b32 s90, s10, 2
	v_ashrrev_i32_e32 v25, 31, v24
	v_lshl_add_u64 v[32:33], v[8:9], 0, s[90:91]
	v_lshlrev_b64 v[24:25], 15, v[24:25]
	v_lshl_add_u64 v[24:25], v[32:33], 0, v[24:25]
	v_add_co_u32_e32 v32, vcc, 0x10000, v24
	global_load_dword v5, v[24:25], off nt
	s_nop 0
	v_addc_co_u32_e32 v33, vcc, 0, v25, vcc
	global_load_dword v11, v[32:33], off nt
	v_add_co_u32_e32 v32, vcc, 0x20000, v24
	s_lshl_b32 s90, s11, 1
	s_nop 0
	v_addc_co_u32_e32 v33, vcc, 0, v25, vcc
	global_load_dword v18, v[32:33], off nt
	v_add_co_u32_e32 v32, vcc, 0x30000, v24
	s_nop 1
	v_addc_co_u32_e32 v33, vcc, 0, v25, vcc
	global_load_dword v31, v[32:33], off nt
	v_add_co_u32_e32 v32, vcc, 0x40000, v24
	s_nop 1
	v_addc_co_u32_e32 v33, vcc, 0, v25, vcc
	global_load_dword v34, v[32:33], off nt
	v_add_co_u32_e32 v32, vcc, 0x50000, v24
	s_nop 1
	v_addc_co_u32_e32 v33, vcc, 0, v25, vcc
	global_load_dword v35, v[32:33], off nt
	v_add_co_u32_e32 v32, vcc, 0x60000, v24
	s_nop 1
	v_addc_co_u32_e32 v33, vcc, 0, v25, vcc
	global_load_dword v36, v[32:33], off nt
	v_add_co_u32_e32 v32, vcc, 0x70000, v24
	s_nop 1
	v_addc_co_u32_e32 v33, vcc, 0, v25, vcc
	global_load_dword v37, v[32:33], off nt
	v_add_co_u32_e32 v32, vcc, 0x80000, v24
	s_nop 1
	v_addc_co_u32_e32 v33, vcc, 0, v25, vcc
	global_load_dword v38, v[32:33], off nt
	v_add_co_u32_e32 v32, vcc, 0x90000, v24
	s_nop 1
	v_addc_co_u32_e32 v33, vcc, 0, v25, vcc
	global_load_dword v39, v[32:33], off nt
	v_add_co_u32_e32 v32, vcc, 0xa0000, v24
	s_nop 1
	v_addc_co_u32_e32 v33, vcc, 0, v25, vcc
	global_load_dword v40, v[32:33], off nt
	v_add_co_u32_e32 v32, vcc, 0xb0000, v24
	s_nop 1
	v_addc_co_u32_e32 v33, vcc, 0, v25, vcc
	global_load_dword v41, v[32:33], off nt
	v_add_co_u32_e32 v32, vcc, 0xc0000, v24
	s_nop 1
	v_addc_co_u32_e32 v33, vcc, 0, v25, vcc
	global_load_dword v42, v[32:33], off nt
	v_add_co_u32_e32 v32, vcc, 0xd0000, v24
	s_nop 1
	v_addc_co_u32_e32 v33, vcc, 0, v25, vcc
	global_load_dword v43, v[32:33], off nt
	v_add_co_u32_e32 v32, vcc, 0xe0000, v24
	s_nop 1
	v_addc_co_u32_e32 v33, vcc, 0, v25, vcc
	global_load_dword v44, v[32:33], off nt
	v_add_co_u32_e32 v32, vcc, 0xf0000, v24
	s_nop 1
	v_addc_co_u32_e32 v33, vcc, 0, v25, vcc
	global_load_dword v45, v[32:33], off nt
	v_add_co_u32_e32 v32, vcc, 0x100000, v24
	s_nop 1
	v_addc_co_u32_e32 v33, vcc, 0, v25, vcc
	global_load_dword v46, v[32:33], off nt
	v_add_co_u32_e32 v32, vcc, 0x110000, v24
	s_nop 1
	v_addc_co_u32_e32 v33, vcc, 0, v25, vcc
	global_load_dword v47, v[32:33], off nt
	v_add_co_u32_e32 v32, vcc, 0x120000, v24
	s_nop 1
	v_addc_co_u32_e32 v33, vcc, 0, v25, vcc
	global_load_dword v48, v[32:33], off nt
	v_add_co_u32_e32 v32, vcc, 0x130000, v24
	s_nop 1
	v_addc_co_u32_e32 v33, vcc, 0, v25, vcc
	global_load_dword v49, v[32:33], off nt
	v_add_co_u32_e32 v32, vcc, 0x140000, v24
	s_nop 1
	v_addc_co_u32_e32 v33, vcc, 0, v25, vcc
	global_load_dword v50, v[32:33], off nt
	v_add_co_u32_e32 v32, vcc, 0x150000, v24
	s_nop 1
	v_addc_co_u32_e32 v33, vcc, 0, v25, vcc
	global_load_dword v51, v[32:33], off nt
	v_add_co_u32_e32 v32, vcc, 0x160000, v24
	s_nop 1
	v_addc_co_u32_e32 v33, vcc, 0, v25, vcc
	global_load_dword v52, v[32:33], off nt
	v_add_co_u32_e32 v32, vcc, 0x170000, v24
	s_nop 1
	v_addc_co_u32_e32 v33, vcc, 0, v25, vcc
	global_load_dword v53, v[32:33], off nt
	v_add_co_u32_e32 v32, vcc, 0x180000, v24
	s_nop 1
	v_addc_co_u32_e32 v33, vcc, 0, v25, vcc
	global_load_dword v54, v[32:33], off nt
	v_add_co_u32_e32 v32, vcc, 0x190000, v24
	s_nop 1
	v_addc_co_u32_e32 v33, vcc, 0, v25, vcc
	global_load_dword v55, v[32:33], off nt
	v_add_co_u32_e32 v32, vcc, 0x1a0000, v24
	s_nop 1
	v_addc_co_u32_e32 v33, vcc, 0, v25, vcc
	global_load_dword v56, v[32:33], off nt
	v_add_co_u32_e32 v32, vcc, 0x1b0000, v24
	s_nop 1
	v_addc_co_u32_e32 v33, vcc, 0, v25, vcc
	global_load_dword v57, v[32:33], off nt
	v_add_co_u32_e32 v32, vcc, 0x1c0000, v24
	s_nop 1
	v_addc_co_u32_e32 v33, vcc, 0, v25, vcc
	global_load_dword v58, v[32:33], off nt
	v_add_co_u32_e32 v32, vcc, 0x1d0000, v24
	s_nop 1
	v_addc_co_u32_e32 v33, vcc, 0, v25, vcc
	global_load_dword v59, v[32:33], off nt
	v_add_co_u32_e32 v32, vcc, 0x1e0000, v24
	s_nop 1
	v_addc_co_u32_e32 v33, vcc, 0, v25, vcc
	v_add_co_u32_e32 v24, vcc, 0x1f0000, v24
	global_load_dword v32, v[32:33], off nt
	s_nop 0
	v_addc_co_u32_e32 v25, vcc, 0, v25, vcc
	global_load_dword v24, v[24:25], off nt
	s_waitcnt vmcnt(0)
	ds_write2_b32 v3, v5, v11 offset1:66
	ds_write2_b32 v3, v18, v31 offset0:132 offset1:198
	v_add_u32_e32 v5, 0x400, v3
	ds_write2_b32 v5, v34, v35 offset0:8 offset1:74
	ds_write2_b32 v5, v36, v37 offset0:140 offset1:206
	v_add_u32_e32 v5, 0x800, v3
	ds_write2_b32 v5, v38, v39 offset0:16 offset1:82
	ds_write2_b32 v5, v40, v41 offset0:148 offset1:214
	v_add_u32_e32 v5, 0xc00, v3
	ds_write2_b32 v5, v42, v43 offset0:24 offset1:90
	ds_write2_b32 v5, v44, v45 offset0:156 offset1:222
	v_add_u32_e32 v5, 0x1000, v3
	ds_write2_b32 v5, v46, v47 offset0:32 offset1:98
	ds_write2_b32 v5, v48, v49 offset0:164 offset1:230
	v_add_u32_e32 v5, 0x1400, v3
	ds_write2_b32 v5, v50, v51 offset0:40 offset1:106
	ds_write2_b32 v5, v52, v53 offset0:172 offset1:238
	v_add_u32_e32 v5, 0x1800, v3
	ds_write2_b32 v5, v54, v55 offset0:48 offset1:114
	ds_write2_b32 v5, v56, v57 offset0:180 offset1:246
	v_add_u32_e32 v5, 0x1c00, v3
	ds_write2_b32 v5, v58, v59 offset0:56 offset1:122
	ds_write2_b32 v5, v32, v24 offset0:188 offset1:254
	s_waitcnt lgkmcnt(0)
	ds_read2_b32 v[36:37], v27 offset0:33 offset1:41
	ds_read2_b32 v[38:39], v27 offset1:8
	ds_read2_b32 v[40:41], v27 offset0:66 offset1:74
	ds_read2_b32 v[42:43], v27 offset0:99 offset1:107
	ds_read2_b32 v[44:45], v27 offset0:132 offset1:140
	ds_read2_b32 v[46:47], v27 offset0:165 offset1:173
	ds_read2_b32 v[48:49], v27 offset0:198 offset1:206
	ds_read2_b32 v[50:51], v27 offset0:231 offset1:239
	s_waitcnt lgkmcnt(7)
	v_bfe_u32 v11, v36, 16, 1
	s_waitcnt lgkmcnt(6)
	v_bfe_u32 v5, v38, 16, 1
	v_add3_u32 v5, v38, v5, s79
	v_lshrrev_b32_e32 v5, 16, v5
	v_add3_u32 v11, v36, v11, s79
	v_and_or_b32 v32, v11, s80, v5
	s_waitcnt lgkmcnt(5)
	v_bfe_u32 v5, v40, 16, 1
	v_add3_u32 v5, v40, v5, s79
	s_waitcnt lgkmcnt(4)
	v_bfe_u32 v11, v42, 16, 1
	v_lshrrev_b32_e32 v5, 16, v5
	v_add3_u32 v11, v42, v11, s79
	v_and_or_b32 v33, v11, s80, v5
	s_waitcnt lgkmcnt(3)
	v_bfe_u32 v5, v44, 16, 1
	v_add3_u32 v5, v44, v5, s79
	s_waitcnt lgkmcnt(2)
	v_bfe_u32 v11, v46, 16, 1
	v_lshrrev_b32_e32 v5, 16, v5
	v_add3_u32 v11, v46, v11, s79
	v_and_or_b32 v34, v11, s80, v5
	s_waitcnt lgkmcnt(1)
	v_bfe_u32 v5, v48, 16, 1
	v_add3_u32 v5, v48, v5, s79
	s_waitcnt lgkmcnt(0)
	v_bfe_u32 v11, v50, 16, 1
	v_lshrrev_b32_e32 v5, 16, v5
	v_add3_u32 v11, v50, v11, s79
	v_add_u32_e32 v52, s10, v26
	v_and_or_b32 v35, v11, s80, v5
	v_ashrrev_i32_e32 v53, 31, v52
	v_bfe_u32 v5, v39, 16, 1
	v_lshl_add_u64 v[24:25], v[12:13], 0, s[90:91]
	v_lshlrev_b64 v[52:53], 12, v[52:53]
	v_add3_u32 v5, v39, v5, s79
	v_bfe_u32 v11, v37, 16, 1
	v_lshl_add_u64 v[52:53], v[24:25], 0, v[52:53]
	v_lshrrev_b32_e32 v5, 16, v5
	v_add3_u32 v11, v37, v11, s79
	global_store_dwordx4 v[52:53], v[32:35], off
	v_add_u32_e32 v36, s10, v28
	v_ashrrev_i32_e32 v37, 31, v36
	v_and_or_b32 v32, v11, s80, v5
	v_bfe_u32 v5, v41, 16, 1
	v_add3_u32 v5, v41, v5, s79
	v_bfe_u32 v11, v43, 16, 1
	v_lshrrev_b32_e32 v5, 16, v5
	v_add3_u32 v11, v43, v11, s79
	v_and_or_b32 v33, v11, s80, v5
	v_bfe_u32 v5, v45, 16, 1
	v_add3_u32 v5, v45, v5, s79
	v_bfe_u32 v11, v47, 16, 1
	v_lshrrev_b32_e32 v5, 16, v5
	v_add3_u32 v11, v47, v11, s79
	v_and_or_b32 v34, v11, s80, v5
	v_bfe_u32 v5, v49, 16, 1
	v_add3_u32 v5, v49, v5, s79
	v_bfe_u32 v11, v51, 16, 1
	v_lshrrev_b32_e32 v5, 16, v5
	v_add3_u32 v11, v51, v11, s79
	v_lshlrev_b64 v[36:37], 12, v[36:37]
	v_and_or_b32 v35, v11, s80, v5
	v_lshl_add_u64 v[36:37], v[24:25], 0, v[36:37]
	global_store_dwordx4 v[36:37], v[32:35], off
	ds_read2_b32 v[36:37], v27 offset0:49 offset1:57
	ds_read2_b32 v[38:39], v27 offset0:16 offset1:24
	ds_read2_b32 v[40:41], v27 offset0:82 offset1:90
	ds_read2_b32 v[42:43], v27 offset0:115 offset1:123
	ds_read2_b32 v[44:45], v27 offset0:148 offset1:156
	ds_read2_b32 v[46:47], v27 offset0:181 offset1:189
	ds_read2_b32 v[48:49], v27 offset0:214 offset1:222
	ds_read2_b32 v[50:51], v27 offset0:247 offset1:255
	s_waitcnt lgkmcnt(7)
	v_bfe_u32 v11, v36, 16, 1
	s_waitcnt lgkmcnt(6)
	v_bfe_u32 v5, v38, 16, 1
	v_add3_u32 v5, v38, v5, s79
	v_lshrrev_b32_e32 v5, 16, v5
	v_add3_u32 v11, v36, v11, s79
	v_and_or_b32 v32, v11, s80, v5
	s_waitcnt lgkmcnt(5)
	v_bfe_u32 v5, v40, 16, 1
	v_add3_u32 v5, v40, v5, s79
	s_waitcnt lgkmcnt(4)
	v_bfe_u32 v11, v42, 16, 1
	v_lshrrev_b32_e32 v5, 16, v5
	v_add3_u32 v11, v42, v11, s79
	v_and_or_b32 v33, v11, s80, v5
	s_waitcnt lgkmcnt(3)
	v_bfe_u32 v5, v44, 16, 1
	v_add3_u32 v5, v44, v5, s79
	s_waitcnt lgkmcnt(2)
	v_bfe_u32 v11, v46, 16, 1
	v_lshrrev_b32_e32 v5, 16, v5
	v_add3_u32 v11, v46, v11, s79
	v_and_or_b32 v34, v11, s80, v5
	s_waitcnt lgkmcnt(1)
	v_bfe_u32 v5, v48, 16, 1
	v_add3_u32 v5, v48, v5, s79
	s_waitcnt lgkmcnt(0)
	v_bfe_u32 v11, v50, 16, 1
	v_lshrrev_b32_e32 v5, 16, v5
	v_add3_u32 v11, v50, v11, s79
	v_add_u32_e32 v52, s10, v29
	v_and_or_b32 v35, v11, s80, v5
	v_ashrrev_i32_e32 v53, 31, v52
	v_bfe_u32 v5, v39, 16, 1
	v_lshlrev_b64 v[52:53], 12, v[52:53]
	v_add3_u32 v5, v39, v5, s79
	v_bfe_u32 v11, v37, 16, 1
	v_lshl_add_u64 v[52:53], v[24:25], 0, v[52:53]
	v_lshrrev_b32_e32 v5, 16, v5
	v_add3_u32 v11, v37, v11, s79
	global_store_dwordx4 v[52:53], v[32:35], off
	v_add_u32_e32 v36, s10, v30
	v_ashrrev_i32_e32 v37, 31, v36
	v_and_or_b32 v32, v11, s80, v5
	v_bfe_u32 v5, v41, 16, 1
	v_add3_u32 v5, v41, v5, s79
	v_bfe_u32 v11, v43, 16, 1
	v_lshrrev_b32_e32 v5, 16, v5
	v_add3_u32 v11, v43, v11, s79
	v_and_or_b32 v33, v11, s80, v5
	v_bfe_u32 v5, v45, 16, 1
	v_add3_u32 v5, v45, v5, s79
	v_bfe_u32 v11, v47, 16, 1
	v_lshrrev_b32_e32 v5, 16, v5
	v_add3_u32 v11, v47, v11, s79
	v_and_or_b32 v34, v11, s80, v5
	v_bfe_u32 v5, v49, 16, 1
	v_add3_u32 v5, v49, v5, s79
	v_bfe_u32 v11, v51, 16, 1
	v_lshrrev_b32_e32 v5, 16, v5
	v_add3_u32 v11, v51, v11, s79
	v_lshlrev_b64 v[36:37], 12, v[36:37]
	v_and_or_b32 v35, v11, s80, v5
	v_lshl_add_u64 v[24:25], v[24:25], 0, v[36:37]
	global_store_dwordx4 v[24:25], v[32:35], off
	s_waitcnt lgkmcnt(0)

.LBB0_1784:
	s_andn2_b64 vcc, exec, s[10:11]
	s_cbranch_vccnz .LBB0_1786
	s_and_b32 s10, s13, 0x1fc0
	s_addk_i32 s10, 0xed00
	s_lshl_b32 s11, s13, 5
	s_and_b32 s14, s11, 0x7e0
	v_add_u32_e32 v24, s10, v1
	s_lshl_b32 s90, s14, 2
	v_ashrrev_i32_e32 v25, 31, v24
	v_lshl_add_u64 v[32:33], v[14:15], 0, s[90:91]
	v_lshlrev_b64 v[24:25], 13, v[24:25]
	v_lshl_add_u64 v[24:25], v[32:33], 0, v[24:25]
	v_add_co_u32_e32 v32, vcc, 0x4000, v24
	global_load_dword v5, v[24:25], off nt
	s_nop 0
	v_addc_co_u32_e32 v33, vcc, 0, v25, vcc
	global_load_dword v11, v[32:33], off nt
	v_add_co_u32_e32 v32, vcc, 0x8000, v24
	s_mov_b32 s11, 0xc000
	s_nop 0
	v_addc_co_u32_e32 v33, vcc, 0, v25, vcc
	global_load_dword v18, v[32:33], off nt
	v_add_co_u32_e32 v32, vcc, s11, v24
	s_mov_b32 s11, 0x10000
	s_nop 0
	v_addc_co_u32_e32 v33, vcc, 0, v25, vcc
	global_load_dword v31, v[32:33], off nt
	v_add_co_u32_e32 v32, vcc, s11, v24
	s_mov_b32 s11, 0x14000
	s_nop 0
	v_addc_co_u32_e32 v33, vcc, 0, v25, vcc
	global_load_dword v34, v[32:33], off nt
	v_add_co_u32_e32 v32, vcc, s11, v24
	s_mov_b32 s11, 0x18000
	s_nop 0
	v_addc_co_u32_e32 v33, vcc, 0, v25, vcc
	global_load_dword v35, v[32:33], off nt
	v_add_co_u32_e32 v32, vcc, s11, v24
	s_mov_b32 s11, 0x1c000
	s_nop 0
	v_addc_co_u32_e32 v33, vcc, 0, v25, vcc
	global_load_dword v36, v[32:33], off nt
	v_add_co_u32_e32 v32, vcc, s11, v24
	s_mov_b32 s11, 0x20000
	s_nop 0
	v_addc_co_u32_e32 v33, vcc, 0, v25, vcc
	global_load_dword v37, v[32:33], off nt
	v_add_co_u32_e32 v32, vcc, s11, v24
	s_mov_b32 s11, 0x58000
	s_nop 0
	v_addc_co_u32_e32 v33, vcc, 0, v25, vcc
	global_load_dword v38, v[32:33], off nt
	v_add_co_u32_e32 v32, vcc, s19, v24
	s_nop 1
	v_addc_co_u32_e32 v33, vcc, 0, v25, vcc
	global_load_dword v39, v[32:33], off nt
	v_add_co_u32_e32 v32, vcc, s20, v24
	s_nop 1
	v_addc_co_u32_e32 v33, vcc, 0, v25, vcc
	global_load_dword v40, v[32:33], off nt
	v_add_co_u32_e32 v32, vcc, s21, v24
	s_nop 1
	v_addc_co_u32_e32 v33, vcc, 0, v25, vcc
	global_load_dword v41, v[32:33], off nt
	v_add_co_u32_e32 v32, vcc, s22, v24
	s_nop 1
	v_addc_co_u32_e32 v33, vcc, 0, v25, vcc
	global_load_dword v42, v[32:33], off nt
	v_add_co_u32_e32 v32, vcc, s23, v24
	s_nop 1
	v_addc_co_u32_e32 v33, vcc, 0, v25, vcc
	global_load_dword v43, v[32:33], off nt
	v_add_co_u32_e32 v32, vcc, s24, v24
	s_nop 1
	v_addc_co_u32_e32 v33, vcc, 0, v25, vcc
	global_load_dword v44, v[32:33], off nt
	v_add_co_u32_e32 v32, vcc, s25, v24
	s_nop 1
	v_addc_co_u32_e32 v33, vcc, 0, v25, vcc
	global_load_dword v45, v[32:33], off nt
	v_add_co_u32_e32 v32, vcc, s26, v24
	s_nop 1
	v_addc_co_u32_e32 v33, vcc, 0, v25, vcc
	global_load_dword v46, v[32:33], off nt
	v_add_co_u32_e32 v32, vcc, s27, v24
	s_nop 1
	v_addc_co_u32_e32 v33, vcc, 0, v25, vcc
	global_load_dword v47, v[32:33], off nt
	v_add_co_u32_e32 v32, vcc, s43, v24
	s_nop 1
	v_addc_co_u32_e32 v33, vcc, 0, v25, vcc
	global_load_dword v48, v[32:33], off nt
	v_add_co_u32_e32 v32, vcc, s44, v24
	s_nop 1
	v_addc_co_u32_e32 v33, vcc, 0, v25, vcc
	global_load_dword v49, v[32:33], off nt
	v_add_co_u32_e32 v32, vcc, s45, v24
	s_nop 1
	v_addc_co_u32_e32 v33, vcc, 0, v25, vcc
	global_load_dword v50, v[32:33], off nt
	v_add_co_u32_e32 v32, vcc, s46, v24
	s_nop 1
	v_addc_co_u32_e32 v33, vcc, 0, v25, vcc
	global_load_dword v51, v[32:33], off nt
	v_add_co_u32_e32 v32, vcc, s11, v24
	s_mov_b32 s11, 0x5c000
	s_nop 0
	v_addc_co_u32_e32 v33, vcc, 0, v25, vcc
	global_load_dword v52, v[32:33], off nt
	v_add_co_u32_e32 v32, vcc, s11, v24
	s_mov_b32 s11, 0x60000
	s_nop 0
	v_addc_co_u32_e32 v33, vcc, 0, v25, vcc
	global_load_dword v53, v[32:33], off nt
	v_add_co_u32_e32 v32, vcc, s11, v24
	s_mov_b32 s11, 0x64000
	s_nop 0
	v_addc_co_u32_e32 v33, vcc, 0, v25, vcc
	global_load_dword v54, v[32:33], off nt
	v_add_co_u32_e32 v32, vcc, s11, v24
	s_mov_b32 s11, 0x68000
	s_nop 0
	v_addc_co_u32_e32 v33, vcc, 0, v25, vcc
	global_load_dword v55, v[32:33], off nt
	v_add_co_u32_e32 v32, vcc, s11, v24
	s_mov_b32 s11, 0x6c000
	s_nop 0
	v_addc_co_u32_e32 v33, vcc, 0, v25, vcc
	global_load_dword v56, v[32:33], off nt
	v_add_co_u32_e32 v32, vcc, s11, v24
	s_mov_b32 s11, 0x70000
	s_nop 0
	v_addc_co_u32_e32 v33, vcc, 0, v25, vcc
	global_load_dword v57, v[32:33], off nt
	v_add_co_u32_e32 v32, vcc, s11, v24
	s_mov_b32 s11, 0x74000
	s_nop 0
	v_addc_co_u32_e32 v33, vcc, 0, v25, vcc
	global_load_dword v58, v[32:33], off nt
	v_add_co_u32_e32 v32, vcc, s11, v24
	s_mov_b32 s11, 0x78000
	s_nop 0
	v_addc_co_u32_e32 v33, vcc, 0, v25, vcc
	global_load_dword v59, v[32:33], off nt
	v_add_co_u32_e32 v32, vcc, s11, v24
	s_mov_b32 s11, 0x7c000
	s_nop 0
	v_addc_co_u32_e32 v33, vcc, 0, v25, vcc
	v_add_co_u32_e32 v24, vcc, s11, v24
	global_load_dword v32, v[32:33], off nt
	s_nop 0
	v_addc_co_u32_e32 v25, vcc, 0, v25, vcc
	global_load_dword v24, v[24:25], off nt
	s_waitcnt vmcnt(0)
	ds_write2_b32 v3, v5, v11 offset1:66
	ds_write2_b32 v3, v18, v31 offset0:132 offset1:198
	v_add_u32_e32 v5, 0x400, v3
	ds_write2_b32 v5, v34, v35 offset0:8 offset1:74
	ds_write2_b32 v5, v36, v37 offset0:140 offset1:206
	v_add_u32_e32 v5, 0x800, v3
	ds_write2_b32 v5, v38, v39 offset0:16 offset1:82
	ds_write2_b32 v5, v40, v41 offset0:148 offset1:214
	v_add_u32_e32 v5, 0xc00, v3
	ds_write2_b32 v5, v42, v43 offset0:24 offset1:90
	ds_write2_b32 v5, v44, v45 offset0:156 offset1:222
	v_add_u32_e32 v5, 0x1000, v3
	ds_write2_b32 v5, v46, v47 offset0:32 offset1:98
	ds_write2_b32 v5, v48, v49 offset0:164 offset1:230
	v_add_u32_e32 v5, 0x1400, v3
	ds_write2_b32 v5, v50, v51 offset0:40 offset1:106
	ds_write2_b32 v5, v52, v53 offset0:172 offset1:238
	v_add_u32_e32 v5, 0x1800, v3
	ds_write2_b32 v5, v54, v55 offset0:48 offset1:114
	ds_write2_b32 v5, v56, v57 offset0:180 offset1:246
	v_add_u32_e32 v5, 0x1c00, v3
	ds_write2_b32 v5, v58, v59 offset0:56 offset1:122
	ds_write2_b32 v5, v32, v24 offset0:188 offset1:254
	s_waitcnt lgkmcnt(0)
	ds_read2_b32 v[36:37], v27 offset0:33 offset1:41
	ds_read2_b32 v[38:39], v27 offset1:8
	ds_read2_b32 v[40:41], v27 offset0:66 offset1:74
	ds_read2_b32 v[42:43], v27 offset0:99 offset1:107
	ds_read2_b32 v[44:45], v27 offset0:132 offset1:140
	ds_read2_b32 v[46:47], v27 offset0:165 offset1:173
	ds_read2_b32 v[48:49], v27 offset0:198 offset1:206
	ds_read2_b32 v[50:51], v27 offset0:231 offset1:239
	s_waitcnt lgkmcnt(7)
	v_bfe_u32 v11, v36, 16, 1
	s_waitcnt lgkmcnt(6)
	v_bfe_u32 v5, v38, 16, 1
	v_add3_u32 v5, v38, v5, s79
	v_lshrrev_b32_e32 v5, 16, v5
	v_add3_u32 v11, v36, v11, s79
	v_and_or_b32 v32, v11, s80, v5
	s_waitcnt lgkmcnt(5)
	v_bfe_u32 v5, v40, 16, 1
	v_add3_u32 v5, v40, v5, s79
	s_waitcnt lgkmcnt(4)
	v_bfe_u32 v11, v42, 16, 1
	v_lshrrev_b32_e32 v5, 16, v5
	v_add3_u32 v11, v42, v11, s79
	v_and_or_b32 v33, v11, s80, v5
	s_waitcnt lgkmcnt(3)
	v_bfe_u32 v5, v44, 16, 1
	v_add3_u32 v5, v44, v5, s79
	s_waitcnt lgkmcnt(2)
	v_bfe_u32 v11, v46, 16, 1
	v_lshrrev_b32_e32 v5, 16, v5
	v_add3_u32 v11, v46, v11, s79
	v_and_or_b32 v34, v11, s80, v5
	s_waitcnt lgkmcnt(1)
	v_bfe_u32 v5, v48, 16, 1
	v_add3_u32 v5, v48, v5, s79
	s_waitcnt lgkmcnt(0)
	v_bfe_u32 v11, v50, 16, 1
	v_lshrrev_b32_e32 v5, 16, v5
	v_add3_u32 v11, v50, v11, s79
	v_add_u32_e32 v52, s14, v26
	s_mov_b32 s11, s91
	v_and_or_b32 v35, v11, s80, v5
	v_ashrrev_i32_e32 v53, 31, v52
	v_bfe_u32 v5, v39, 16, 1
	v_lshl_add_u64 v[24:25], s[10:11], 1, v[16:17]
	v_lshlrev_b64 v[52:53], 12, v[52:53]
	v_add3_u32 v5, v39, v5, s79
	v_bfe_u32 v11, v37, 16, 1
	v_lshl_add_u64 v[52:53], v[24:25], 0, v[52:53]
	v_lshrrev_b32_e32 v5, 16, v5
	v_add3_u32 v11, v37, v11, s79
	global_store_dwordx4 v[52:53], v[32:35], off
	v_add_u32_e32 v36, s14, v28
	v_ashrrev_i32_e32 v37, 31, v36
	v_and_or_b32 v32, v11, s80, v5
	v_bfe_u32 v5, v41, 16, 1
	v_add3_u32 v5, v41, v5, s79
	v_bfe_u32 v11, v43, 16, 1
	v_lshrrev_b32_e32 v5, 16, v5
	v_add3_u32 v11, v43, v11, s79
	v_and_or_b32 v33, v11, s80, v5
	v_bfe_u32 v5, v45, 16, 1
	v_add3_u32 v5, v45, v5, s79
	v_bfe_u32 v11, v47, 16, 1
	v_lshrrev_b32_e32 v5, 16, v5
	v_add3_u32 v11, v47, v11, s79
	v_and_or_b32 v34, v11, s80, v5
	v_bfe_u32 v5, v49, 16, 1
	v_add3_u32 v5, v49, v5, s79
	v_bfe_u32 v11, v51, 16, 1
	v_lshrrev_b32_e32 v5, 16, v5
	v_add3_u32 v11, v51, v11, s79
	v_lshlrev_b64 v[36:37], 12, v[36:37]
	v_and_or_b32 v35, v11, s80, v5
	v_lshl_add_u64 v[36:37], v[24:25], 0, v[36:37]
	global_store_dwordx4 v[36:37], v[32:35], off
	ds_read2_b32 v[36:37], v27 offset0:49 offset1:57
	ds_read2_b32 v[38:39], v27 offset0:16 offset1:24
	ds_read2_b32 v[40:41], v27 offset0:82 offset1:90
	ds_read2_b32 v[42:43], v27 offset0:115 offset1:123
	ds_read2_b32 v[44:45], v27 offset0:148 offset1:156
	ds_read2_b32 v[46:47], v27 offset0:181 offset1:189
	ds_read2_b32 v[48:49], v27 offset0:214 offset1:222
	ds_read2_b32 v[50:51], v27 offset0:247 offset1:255
	s_waitcnt lgkmcnt(7)
	v_bfe_u32 v11, v36, 16, 1
	s_waitcnt lgkmcnt(6)
	v_bfe_u32 v5, v38, 16, 1
	v_add3_u32 v5, v38, v5, s79
	v_lshrrev_b32_e32 v5, 16, v5
	v_add3_u32 v11, v36, v11, s79
	v_and_or_b32 v32, v11, s80, v5
	s_waitcnt lgkmcnt(5)
	v_bfe_u32 v5, v40, 16, 1
	v_add3_u32 v5, v40, v5, s79
	s_waitcnt lgkmcnt(4)
	v_bfe_u32 v11, v42, 16, 1
	v_lshrrev_b32_e32 v5, 16, v5
	v_add3_u32 v11, v42, v11, s79
	v_and_or_b32 v33, v11, s80, v5
	s_waitcnt lgkmcnt(3)
	v_bfe_u32 v5, v44, 16, 1
	v_add3_u32 v5, v44, v5, s79
	s_waitcnt lgkmcnt(2)
	v_bfe_u32 v11, v46, 16, 1
	v_lshrrev_b32_e32 v5, 16, v5
	v_add3_u32 v11, v46, v11, s79
	v_and_or_b32 v34, v11, s80, v5
	s_waitcnt lgkmcnt(1)
	v_bfe_u32 v5, v48, 16, 1
	v_add3_u32 v5, v48, v5, s79
	s_waitcnt lgkmcnt(0)
	v_bfe_u32 v11, v50, 16, 1
	v_lshrrev_b32_e32 v5, 16, v5
	v_add3_u32 v11, v50, v11, s79
	v_add_u32_e32 v52, s14, v29
	v_and_or_b32 v35, v11, s80, v5
	v_ashrrev_i32_e32 v53, 31, v52
	v_bfe_u32 v5, v39, 16, 1
	v_lshlrev_b64 v[52:53], 12, v[52:53]
	v_add3_u32 v5, v39, v5, s79
	v_bfe_u32 v11, v37, 16, 1
	v_lshl_add_u64 v[52:53], v[24:25], 0, v[52:53]
	v_lshrrev_b32_e32 v5, 16, v5
	v_add3_u32 v11, v37, v11, s79
	global_store_dwordx4 v[52:53], v[32:35], off
	v_add_u32_e32 v36, s14, v30
	v_ashrrev_i32_e32 v37, 31, v36
	v_and_or_b32 v32, v11, s80, v5
	v_bfe_u32 v5, v41, 16, 1
	v_add3_u32 v5, v41, v5, s79
	v_bfe_u32 v11, v43, 16, 1
	v_lshrrev_b32_e32 v5, 16, v5
	v_add3_u32 v11, v43, v11, s79
	v_and_or_b32 v33, v11, s80, v5
	v_bfe_u32 v5, v45, 16, 1
	v_add3_u32 v5, v45, v5, s79
	v_bfe_u32 v11, v47, 16, 1
	v_lshrrev_b32_e32 v5, 16, v5
	v_add3_u32 v11, v47, v11, s79
	v_and_or_b32 v34, v11, s80, v5
	v_bfe_u32 v5, v49, 16, 1
	v_add3_u32 v5, v49, v5, s79
	v_bfe_u32 v11, v51, 16, 1
	v_lshrrev_b32_e32 v5, 16, v5
	v_add3_u32 v11, v51, v11, s79
	v_lshlrev_b64 v[36:37], 12, v[36:37]
	v_and_or_b32 v35, v11, s80, v5
	v_lshl_add_u64 v[24:25], v[24:25], 0, v[36:37]
	global_store_dwordx4 v[24:25], v[32:35], off
	s_waitcnt lgkmcnt(0)

.LBB0_1787:
	s_andn2_b64 vcc, exec, s[10:11]
	s_cbranch_vccnz .LBB0_1775
	s_mul_hi_i32 s10, s13, 0x6bca1af3
	s_lshr_b32 s11, s10, 31
	s_ashr_i32 s10, s10, 6
	s_add_i32 s10, s10, s11
	s_mul_i32 s11, s10, 0x98
	s_sub_i32 s11, s13, s11
	s_lshl_b32 s13, s11, 5
	s_cmpk_gt_i32 s11, 0x7f
	s_cselect_b32 s11, 8, 0
	s_or_b32 s14, s11, s13
	s_lshl_b32 s10, s10, 6
	s_ashr_i32 s15, s14, 31
	v_add_u32_e32 v5, s10, v1
	v_lshl_add_u64 v[24:25], s[14:15], 2, v[20:21]
	v_mad_i64_i32 v[32:33], s[14:15], v5, s37, v[24:25]
	v_add_u32_e32 v18, 2, v5
	global_load_dword v11, v[32:33], off nt
	v_mad_i64_i32 v[32:33], s[14:15], v18, s37, v[24:25]
	v_add_u32_e32 v31, 4, v5
	global_load_dword v18, v[32:33], off nt
	v_mad_i64_i32 v[32:33], s[14:15], v31, s37, v[24:25]
	global_load_dword v31, v[32:33], off nt
	v_add_u32_e32 v32, 6, v5
	v_mad_i64_i32 v[32:33], s[14:15], v32, s37, v[24:25]
	global_load_dword v34, v[32:33], off nt
	v_add_u32_e32 v32, 8, v5
	v_mad_i64_i32 v[32:33], s[14:15], v32, s37, v[24:25]
	global_load_dword v35, v[32:33], off nt
	v_add_u32_e32 v32, 10, v5
	v_mad_i64_i32 v[32:33], s[14:15], v32, s37, v[24:25]
	global_load_dword v36, v[32:33], off nt
	v_add_u32_e32 v32, 12, v5
	v_mad_i64_i32 v[32:33], s[14:15], v32, s37, v[24:25]
	global_load_dword v37, v[32:33], off nt
	v_add_u32_e32 v32, 14, v5
	v_mad_i64_i32 v[32:33], s[14:15], v32, s37, v[24:25]
	global_load_dword v38, v[32:33], off nt
	v_add_u32_e32 v32, 16, v5
	v_mad_i64_i32 v[32:33], s[14:15], v32, s37, v[24:25]
	global_load_dword v39, v[32:33], off nt
	v_add_u32_e32 v32, 18, v5
	v_mad_i64_i32 v[32:33], s[14:15], v32, s37, v[24:25]
	global_load_dword v40, v[32:33], off nt
	v_add_u32_e32 v32, 20, v5
	v_mad_i64_i32 v[32:33], s[14:15], v32, s37, v[24:25]
	global_load_dword v41, v[32:33], off nt
	v_add_u32_e32 v32, 22, v5
	v_mad_i64_i32 v[32:33], s[14:15], v32, s37, v[24:25]
	global_load_dword v42, v[32:33], off nt
	v_add_u32_e32 v32, 24, v5
	v_mad_i64_i32 v[32:33], s[14:15], v32, s37, v[24:25]
	global_load_dword v43, v[32:33], off nt
	v_add_u32_e32 v32, 26, v5
	v_mad_i64_i32 v[32:33], s[14:15], v32, s37, v[24:25]
	global_load_dword v44, v[32:33], off nt
	v_add_u32_e32 v32, 28, v5
	v_mad_i64_i32 v[32:33], s[14:15], v32, s37, v[24:25]
	global_load_dword v45, v[32:33], off nt
	v_add_u32_e32 v32, 30, v5
	v_mad_i64_i32 v[32:33], s[14:15], v32, s37, v[24:25]
	global_load_dword v46, v[32:33], off nt
	v_add_u32_e32 v32, 32, v5
	v_mad_i64_i32 v[32:33], s[14:15], v32, s37, v[24:25]
	global_load_dword v47, v[32:33], off nt
	v_add_u32_e32 v32, 34, v5
	v_mad_i64_i32 v[32:33], s[14:15], v32, s37, v[24:25]
	global_load_dword v48, v[32:33], off nt
	v_add_u32_e32 v32, 36, v5
	v_mad_i64_i32 v[32:33], s[14:15], v32, s37, v[24:25]
	global_load_dword v49, v[32:33], off nt
	v_add_u32_e32 v32, 38, v5
	v_mad_i64_i32 v[32:33], s[14:15], v32, s37, v[24:25]
	global_load_dword v50, v[32:33], off nt
	v_add_u32_e32 v32, 40, v5
	v_mad_i64_i32 v[32:33], s[14:15], v32, s37, v[24:25]
	global_load_dword v51, v[32:33], off nt
	v_add_u32_e32 v32, 42, v5
	v_mad_i64_i32 v[32:33], s[14:15], v32, s37, v[24:25]
	global_load_dword v52, v[32:33], off nt
	v_add_u32_e32 v32, 44, v5
	v_mad_i64_i32 v[32:33], s[14:15], v32, s37, v[24:25]
	global_load_dword v53, v[32:33], off nt
	v_add_u32_e32 v32, 46, v5
	v_mad_i64_i32 v[32:33], s[14:15], v32, s37, v[24:25]
	global_load_dword v54, v[32:33], off nt
	v_add_u32_e32 v32, 48, v5
	v_mad_i64_i32 v[32:33], s[14:15], v32, s37, v[24:25]
	global_load_dword v55, v[32:33], off nt
	v_add_u32_e32 v32, 50, v5
	v_mad_i64_i32 v[32:33], s[14:15], v32, s37, v[24:25]
	global_load_dword v56, v[32:33], off nt
	v_add_u32_e32 v32, 52, v5
	v_mad_i64_i32 v[32:33], s[14:15], v32, s37, v[24:25]
	global_load_dword v57, v[32:33], off nt
	v_add_u32_e32 v32, 54, v5
	v_mad_i64_i32 v[32:33], s[14:15], v32, s37, v[24:25]
	global_load_dword v58, v[32:33], off nt
	v_add_u32_e32 v32, 56, v5
	v_mad_i64_i32 v[32:33], s[14:15], v32, s37, v[24:25]
	global_load_dword v59, v[32:33], off nt
	v_add_u32_e32 v32, 58, v5
	v_mad_i64_i32 v[32:33], s[14:15], v32, s37, v[24:25]
	global_load_dword v60, v[32:33], off nt
	v_add_u32_e32 v32, 60, v5
	v_add_u32_e32 v5, 62, v5
	v_mad_i64_i32 v[32:33], s[14:15], v32, s37, v[24:25]
	v_mad_i64_i32 v[24:25], s[14:15], v5, s37, v[24:25]
	global_load_dword v32, v[32:33], off nt
	s_ashr_i32 s11, s10, 31
	global_load_dword v5, v[24:25], off nt
	s_waitcnt vmcnt(0)
	ds_write2_b32 v3, v11, v18 offset1:66
	ds_write2_b32 v3, v31, v34 offset0:132 offset1:198
	v_add_u32_e32 v11, 0x400, v3
	ds_write2_b32 v11, v35, v36 offset0:8 offset1:74
	ds_write2_b32 v11, v37, v38 offset0:140 offset1:206
	v_add_u32_e32 v11, 0x800, v3
	ds_write2_b32 v11, v39, v40 offset0:16 offset1:82
	ds_write2_b32 v11, v41, v42 offset0:148 offset1:214
	v_add_u32_e32 v11, 0xc00, v3
	ds_write2_b32 v11, v43, v44 offset0:24 offset1:90
	ds_write2_b32 v11, v45, v46 offset0:156 offset1:222
	v_add_u32_e32 v11, 0x1000, v3
	ds_write2_b32 v11, v47, v48 offset0:32 offset1:98
	ds_write2_b32 v11, v49, v50 offset0:164 offset1:230
	v_add_u32_e32 v11, 0x1400, v3
	ds_write2_b32 v11, v51, v52 offset0:40 offset1:106
	ds_write2_b32 v11, v53, v54 offset0:172 offset1:238
	v_add_u32_e32 v11, 0x1800, v3
	ds_write2_b32 v11, v55, v56 offset0:48 offset1:114
	ds_write2_b32 v11, v57, v58 offset0:180 offset1:246
	v_add_u32_e32 v11, 0x1c00, v3
	ds_write2_b32 v11, v59, v60 offset0:56 offset1:122
	ds_write2_b32 v11, v32, v5 offset0:188 offset1:254
	s_waitcnt lgkmcnt(0)
	ds_read2_b32 v[36:37], v27 offset0:33 offset1:41
	ds_read2_b32 v[38:39], v27 offset1:8
	ds_read2_b32 v[40:41], v27 offset0:66 offset1:74
	ds_read2_b32 v[42:43], v27 offset0:99 offset1:107
	ds_read2_b32 v[44:45], v27 offset0:132 offset1:140
	ds_read2_b32 v[46:47], v27 offset0:165 offset1:173
	ds_read2_b32 v[48:49], v27 offset0:198 offset1:206
	ds_read2_b32 v[50:51], v27 offset0:231 offset1:239
	s_waitcnt lgkmcnt(7)
	v_bfe_u32 v11, v36, 16, 1
	s_waitcnt lgkmcnt(6)
	v_bfe_u32 v5, v38, 16, 1
	v_add3_u32 v5, v38, v5, s79
	v_lshrrev_b32_e32 v5, 16, v5
	v_add3_u32 v11, v36, v11, s79
	v_and_or_b32 v32, v11, s80, v5
	s_waitcnt lgkmcnt(5)
	v_bfe_u32 v5, v40, 16, 1
	v_add3_u32 v5, v40, v5, s79
	s_waitcnt lgkmcnt(4)
	v_bfe_u32 v11, v42, 16, 1
	v_lshrrev_b32_e32 v5, 16, v5
	v_add3_u32 v11, v42, v11, s79
	v_and_or_b32 v33, v11, s80, v5
	s_waitcnt lgkmcnt(3)
	v_bfe_u32 v5, v44, 16, 1
	v_add3_u32 v5, v44, v5, s79
	s_waitcnt lgkmcnt(2)
	v_bfe_u32 v11, v46, 16, 1
	v_lshrrev_b32_e32 v5, 16, v5
	v_add3_u32 v11, v46, v11, s79
	v_and_or_b32 v34, v11, s80, v5
	s_waitcnt lgkmcnt(1)
	v_bfe_u32 v5, v48, 16, 1
	v_add3_u32 v5, v48, v5, s79
	s_waitcnt lgkmcnt(0)
	v_bfe_u32 v11, v50, 16, 1
	v_lshrrev_b32_e32 v5, 16, v5
	v_add3_u32 v11, v50, v11, s79
	v_add_u32_e32 v52, s13, v26
	v_and_or_b32 v35, v11, s80, v5
	v_ashrrev_i32_e32 v53, 31, v52
	v_bfe_u32 v5, v39, 16, 1
	v_lshl_add_u64 v[24:25], s[10:11], 1, v[22:23]
	v_lshlrev_b64 v[52:53], 12, v[52:53]
	v_add3_u32 v5, v39, v5, s79
	v_bfe_u32 v11, v37, 16, 1
	v_lshl_add_u64 v[52:53], v[24:25], 0, v[52:53]
	v_lshrrev_b32_e32 v5, 16, v5
	v_add3_u32 v11, v37, v11, s79
	global_store_dwordx4 v[52:53], v[32:35], off
	v_add_u32_e32 v36, s13, v28
	v_ashrrev_i32_e32 v37, 31, v36
	v_and_or_b32 v32, v11, s80, v5
	v_bfe_u32 v5, v41, 16, 1
	v_add3_u32 v5, v41, v5, s79
	v_bfe_u32 v11, v43, 16, 1
	v_lshrrev_b32_e32 v5, 16, v5
	v_add3_u32 v11, v43, v11, s79
	v_and_or_b32 v33, v11, s80, v5
	v_bfe_u32 v5, v45, 16, 1
	v_add3_u32 v5, v45, v5, s79
	v_bfe_u32 v11, v47, 16, 1
	v_lshrrev_b32_e32 v5, 16, v5
	v_add3_u32 v11, v47, v11, s79
	v_and_or_b32 v34, v11, s80, v5
	v_bfe_u32 v5, v49, 16, 1
	v_add3_u32 v5, v49, v5, s79
	v_bfe_u32 v11, v51, 16, 1
	v_lshrrev_b32_e32 v5, 16, v5
	v_add3_u32 v11, v51, v11, s79
	v_lshlrev_b64 v[36:37], 12, v[36:37]
	v_and_or_b32 v35, v11, s80, v5
	v_lshl_add_u64 v[36:37], v[24:25], 0, v[36:37]
	global_store_dwordx4 v[36:37], v[32:35], off
	ds_read2_b32 v[36:37], v27 offset0:49 offset1:57
	ds_read2_b32 v[38:39], v27 offset0:16 offset1:24
	ds_read2_b32 v[40:41], v27 offset0:82 offset1:90
	ds_read2_b32 v[42:43], v27 offset0:115 offset1:123
	ds_read2_b32 v[44:45], v27 offset0:148 offset1:156
	ds_read2_b32 v[46:47], v27 offset0:181 offset1:189
	ds_read2_b32 v[48:49], v27 offset0:214 offset1:222
	ds_read2_b32 v[50:51], v27 offset0:247 offset1:255
	s_waitcnt lgkmcnt(7)
	v_bfe_u32 v11, v36, 16, 1
	s_waitcnt lgkmcnt(6)
	v_bfe_u32 v5, v38, 16, 1
	v_add3_u32 v5, v38, v5, s79
	v_lshrrev_b32_e32 v5, 16, v5
	v_add3_u32 v11, v36, v11, s79
	v_and_or_b32 v32, v11, s80, v5
	s_waitcnt lgkmcnt(5)
	v_bfe_u32 v5, v40, 16, 1
	v_add3_u32 v5, v40, v5, s79
	s_waitcnt lgkmcnt(4)
	v_bfe_u32 v11, v42, 16, 1
	v_lshrrev_b32_e32 v5, 16, v5
	v_add3_u32 v11, v42, v11, s79
	v_and_or_b32 v33, v11, s80, v5
	s_waitcnt lgkmcnt(3)
	v_bfe_u32 v5, v44, 16, 1
	v_add3_u32 v5, v44, v5, s79
	s_waitcnt lgkmcnt(2)
	v_bfe_u32 v11, v46, 16, 1
	v_lshrrev_b32_e32 v5, 16, v5
	v_add3_u32 v11, v46, v11, s79
	v_and_or_b32 v34, v11, s80, v5
	s_waitcnt lgkmcnt(1)
	v_bfe_u32 v5, v48, 16, 1
	v_add3_u32 v5, v48, v5, s79
	s_waitcnt lgkmcnt(0)
	v_bfe_u32 v11, v50, 16, 1
	v_lshrrev_b32_e32 v5, 16, v5
	v_add3_u32 v11, v50, v11, s79
	v_add_u32_e32 v52, s13, v29
	v_and_or_b32 v35, v11, s80, v5
	v_ashrrev_i32_e32 v53, 31, v52
	v_bfe_u32 v5, v39, 16, 1
	v_lshlrev_b64 v[52:53], 12, v[52:53]
	v_add3_u32 v5, v39, v5, s79
	v_bfe_u32 v11, v37, 16, 1
	v_lshl_add_u64 v[52:53], v[24:25], 0, v[52:53]
	v_lshrrev_b32_e32 v5, 16, v5
	v_add3_u32 v11, v37, v11, s79
	global_store_dwordx4 v[52:53], v[32:35], off
	v_add_u32_e32 v36, s13, v30
	v_ashrrev_i32_e32 v37, 31, v36
	v_and_or_b32 v32, v11, s80, v5
	v_bfe_u32 v5, v41, 16, 1
	v_add3_u32 v5, v41, v5, s79
	v_bfe_u32 v11, v43, 16, 1
	v_lshrrev_b32_e32 v5, 16, v5
	v_add3_u32 v11, v43, v11, s79
	v_and_or_b32 v33, v11, s80, v5
	v_bfe_u32 v5, v45, 16, 1
	v_add3_u32 v5, v45, v5, s79
	v_bfe_u32 v11, v47, 16, 1
	v_lshrrev_b32_e32 v5, 16, v5
	v_add3_u32 v11, v47, v11, s79
	v_and_or_b32 v34, v11, s80, v5
	v_bfe_u32 v5, v49, 16, 1
	v_add3_u32 v5, v49, v5, s79
	v_bfe_u32 v11, v51, 16, 1
	v_lshrrev_b32_e32 v5, 16, v5
	v_add3_u32 v11, v51, v11, s79
	v_lshlrev_b64 v[36:37], 12, v[36:37]
	v_and_or_b32 v35, v11, s80, v5
	v_lshl_add_u64 v[24:25], v[24:25], 0, v[36:37]
	global_store_dwordx4 v[24:25], v[32:35], off
	s_waitcnt lgkmcnt(0)
	s_branch .LBB0_1775
